# also D/PLE loops: priority flips deleted and waits merged; loop-exit compare moved into the last MFMA segment (back edge is a lone branch after the barrier)
# baseline (speedup 1.0000x reference)
.LBB0_446:
	s_add_i32 s22, 0, 0x10000
	s_add_i32 s23, 0, 0x14000
	v_add_u32_e32 v134, s22, v191
	v_add_u32_e32 v162, s23, v191
	ds_read_b128 v[114:117], v134
	ds_read_b128 v[126:129], v134 offset:1024
	ds_read_b128 v[130:133], v134 offset:2048
	ds_read_b128 v[134:137], v134 offset:3072
	ds_read_b128 v[146:149], v162
	ds_read_b128 v[150:153], v162 offset:1024
	ds_read_b128 v[158:161], v162 offset:2048
	ds_read_b128 v[182:185], v162 offset:3072
	ds_read_b128 v[186:189], v193
	ds_read_b128 v[194:197], v193 offset:1024
	ds_read_b128 v[198:201], v193 offset:2048
	ds_read_b128 v[214:217], v193 offset:3072
	ds_read_b128 v[218:221], v193 offset:4096
	ds_read_b128 v[222:225], v193 offset:5120
	ds_read_b128 v[226:229], v193 offset:6144
	ds_read_b128 v[230:233], v193 offset:7168
	s_add_u32 s20, s56, 0xfff50080
	s_addc_u32 s21, s57, -1
	s_cmp_eq_u32 s84, 40
	s_cselect_b32 s61, s49, s21
	s_cselect_b32 s60, s48, s20
	s_cselect_b32 s21, s51, s63
	s_cselect_b32 s20, s50, s62
	s_add_i32 m0, s47, 0xc000
	v_lshl_add_u64 v[162:163], s[56:57], 0, v[156:157]
	global_load_lds_dwordx4 v[162:163], off
	v_lshl_add_u64 v[162:163], v[162:163], 0, s[2:3]
	s_add_i32 m0, s47, 0xe000
	s_nop 0
	global_load_lds_dwordx4 v[162:163], off
	s_waitcnt vmcnt(8) lgkmcnt(0)
	s_barrier
	v_mfma_f32_16x16x32_bf16 v[142:145], v[114:117], v[186:189], v[142:145]
	v_mfma_f32_16x16x32_bf16 v[142:145], v[126:129], v[194:197], v[142:145]
	v_mfma_f32_16x16x32_bf16 v[138:141], v[130:133], v[186:189], v[138:141]
	v_mfma_f32_16x16x32_bf16 v[138:141], v[134:137], v[194:197], v[138:141]
	v_mfma_f32_16x16x32_bf16 v[110:113], v[114:117], v[198:201], v[110:113]
	v_mfma_f32_16x16x32_bf16 v[110:113], v[126:129], v[214:217], v[110:113]
	v_mfma_f32_16x16x32_bf16 v[106:109], v[130:133], v[198:201], v[106:109]
	v_mfma_f32_16x16x32_bf16 v[106:109], v[134:137], v[214:217], v[106:109]
	v_mfma_f32_16x16x32_bf16 v[94:97], v[114:117], v[218:221], v[94:97]
	v_mfma_f32_16x16x32_bf16 v[94:97], v[126:129], v[222:225], v[94:97]
	v_mfma_f32_16x16x32_bf16 v[90:93], v[130:133], v[218:221], v[90:93]
	v_mfma_f32_16x16x32_bf16 v[90:93], v[134:137], v[222:225], v[90:93]
	v_mfma_f32_16x16x32_bf16 v[78:81], v[114:117], v[226:229], v[78:81]
	v_mfma_f32_16x16x32_bf16 v[78:81], v[126:129], v[230:233], v[78:81]
	v_mfma_f32_16x16x32_bf16 v[74:77], v[130:133], v[226:229], v[74:77]
	v_mfma_f32_16x16x32_bf16 v[74:77], v[134:137], v[230:233], v[74:77]
	v_mfma_f32_16x16x32_bf16 v[122:125], v[146:149], v[186:189], v[122:125]
	v_mfma_f32_16x16x32_bf16 v[122:125], v[150:153], v[194:197], v[122:125]
	v_mfma_f32_16x16x32_bf16 v[118:121], v[158:161], v[186:189], v[118:121]
	v_mfma_f32_16x16x32_bf16 v[118:121], v[182:185], v[194:197], v[118:121]
	v_mfma_f32_16x16x32_bf16 v[102:105], v[146:149], v[198:201], v[102:105]
	v_mfma_f32_16x16x32_bf16 v[102:105], v[150:153], v[214:217], v[102:105]
	v_mfma_f32_16x16x32_bf16 v[98:101], v[158:161], v[198:201], v[98:101]
	v_mfma_f32_16x16x32_bf16 v[98:101], v[182:185], v[214:217], v[98:101]
	v_mfma_f32_16x16x32_bf16 v[86:89], v[146:149], v[218:221], v[86:89]
	v_mfma_f32_16x16x32_bf16 v[86:89], v[150:153], v[222:225], v[86:89]
	v_mfma_f32_16x16x32_bf16 v[82:85], v[158:161], v[218:221], v[82:85]
	v_mfma_f32_16x16x32_bf16 v[82:85], v[182:185], v[222:225], v[82:85]
	v_mfma_f32_16x16x32_bf16 v[70:73], v[146:149], v[226:229], v[70:73]
	v_mfma_f32_16x16x32_bf16 v[70:73], v[150:153], v[230:233], v[70:73]
	v_mfma_f32_16x16x32_bf16 v[66:69], v[158:161], v[226:229], v[66:69]
	v_mfma_f32_16x16x32_bf16 v[66:69], v[182:185], v[230:233], v[66:69]
	s_barrier
	ds_read_b128 v[186:189], v193 offset:16384
	ds_read_b128 v[194:197], v193 offset:17408
	ds_read_b128 v[198:201], v193 offset:18432
	ds_read_b128 v[214:217], v193 offset:19456
	ds_read_b128 v[218:221], v193 offset:20480
	ds_read_b128 v[222:225], v193 offset:21504
	ds_read_b128 v[226:229], v193 offset:22528
	ds_read_b128 v[230:233], v193 offset:23552
	v_lshl_add_u64 v[162:163], s[20:21], 0, v[0:1]
	s_add_i32 s20, s22, s46
	s_mov_b32 m0, s20
	s_nop 0
	s_nop 0
	global_load_lds_dwordx4 v[162:163], off
	v_lshl_add_u64 v[202:203], v[162:163], 0, s[2:3]
	s_add_i32 m0, s20, 0x2000
	s_add_i32 s20, s23, s46
	global_load_lds_dwordx4 v[202:203], off
	v_lshl_add_u64 v[202:203], v[162:163], 0, s[12:13]
	s_mov_b32 m0, s20
	s_nop 0
	global_load_lds_dwordx4 v[202:203], off
	v_lshl_add_u64 v[202:203], v[162:163], 0, s[86:87]
	s_add_i32 m0, s20, 0x2000
	s_nop 0
	global_load_lds_dwordx4 v[202:203], off
	v_lshl_add_u64 v[202:203], s[60:61], 0, v[154:155]
	s_mov_b32 m0, s47
	v_lshl_add_u64 v[234:235], v[202:203], 0, s[2:3]
	global_load_lds_dwordx4 v[202:203], off
	s_mov_b32 m0, s68
	s_nop 0
	global_load_lds_dwordx4 v[234:235], off
	s_waitcnt vmcnt(8) lgkmcnt(0)
	s_barrier
	v_mfma_f32_16x16x32_bf16 v[62:65], v[114:117], v[186:189], v[62:65]
	v_mfma_f32_16x16x32_bf16 v[62:65], v[126:129], v[194:197], v[62:65]
	v_mfma_f32_16x16x32_bf16 v[58:61], v[130:133], v[186:189], v[58:61]
	v_mfma_f32_16x16x32_bf16 v[58:61], v[134:137], v[194:197], v[58:61]
	v_mfma_f32_16x16x32_bf16 v[46:49], v[114:117], v[198:201], v[46:49]
	v_mfma_f32_16x16x32_bf16 v[46:49], v[126:129], v[214:217], v[46:49]
	v_mfma_f32_16x16x32_bf16 v[42:45], v[130:133], v[198:201], v[42:45]
	v_mfma_f32_16x16x32_bf16 v[42:45], v[134:137], v[214:217], v[42:45]
	v_mfma_f32_16x16x32_bf16 v[30:33], v[114:117], v[218:221], v[30:33]
	v_mfma_f32_16x16x32_bf16 v[30:33], v[126:129], v[222:225], v[30:33]
	v_mfma_f32_16x16x32_bf16 v[26:29], v[130:133], v[218:221], v[26:29]
	v_mfma_f32_16x16x32_bf16 v[26:29], v[134:137], v[222:225], v[26:29]
	v_mfma_f32_16x16x32_bf16 v[14:17], v[114:117], v[226:229], v[14:17]
	v_mfma_f32_16x16x32_bf16 v[14:17], v[126:129], v[230:233], v[14:17]
	v_mfma_f32_16x16x32_bf16 v[10:13], v[130:133], v[226:229], v[10:13]
	v_mfma_f32_16x16x32_bf16 v[10:13], v[134:137], v[230:233], v[10:13]
	v_mfma_f32_16x16x32_bf16 v[54:57], v[146:149], v[186:189], v[54:57]
	v_mfma_f32_16x16x32_bf16 v[54:57], v[150:153], v[194:197], v[54:57]
	v_mfma_f32_16x16x32_bf16 v[50:53], v[158:161], v[186:189], v[50:53]
	v_mfma_f32_16x16x32_bf16 v[50:53], v[182:185], v[194:197], v[50:53]
	v_mfma_f32_16x16x32_bf16 v[38:41], v[146:149], v[198:201], v[38:41]
	v_mfma_f32_16x16x32_bf16 v[38:41], v[150:153], v[214:217], v[38:41]
	v_mfma_f32_16x16x32_bf16 v[34:37], v[158:161], v[198:201], v[34:37]
	v_mfma_f32_16x16x32_bf16 v[34:37], v[182:185], v[214:217], v[34:37]
	v_mfma_f32_16x16x32_bf16 v[22:25], v[146:149], v[218:221], v[22:25]
	v_mfma_f32_16x16x32_bf16 v[22:25], v[150:153], v[222:225], v[22:25]
	v_mfma_f32_16x16x32_bf16 v[18:21], v[158:161], v[218:221], v[18:21]
	v_mfma_f32_16x16x32_bf16 v[18:21], v[182:185], v[222:225], v[18:21]
	v_mfma_f32_16x16x32_bf16 v[6:9], v[146:149], v[226:229], v[6:9]
	v_mfma_f32_16x16x32_bf16 v[6:9], v[150:153], v[230:233], v[6:9]
	v_mfma_f32_16x16x32_bf16 v[2:5], v[158:161], v[226:229], v[2:5]
	v_mfma_f32_16x16x32_bf16 v[2:5], v[182:185], v[230:233], v[2:5]
	s_barrier
	s_add_i32 s20, 0, 0x18000
	s_add_i32 s21, 0, 0x1c000
	v_add_u32_e32 v134, s20, v191
	v_add_u32_e32 v182, s21, v191
	ds_read_b128 v[114:117], v134
	ds_read_b128 v[126:129], v134 offset:1024
	ds_read_b128 v[130:133], v134 offset:2048
	ds_read_b128 v[134:137], v134 offset:3072
	ds_read_b128 v[146:149], v182
	ds_read_b128 v[150:153], v182 offset:1024
	ds_read_b128 v[158:161], v182 offset:2048
	ds_read_b128 v[182:185], v182 offset:3072
	ds_read_b128 v[186:189], v193 offset:32768
	ds_read_b128 v[194:197], v193 offset:33792
	ds_read_b128 v[198:201], v193 offset:34816
	ds_read_b128 v[214:217], v193 offset:35840
	ds_read_b128 v[218:221], v193 offset:36864
	ds_read_b128 v[222:225], v193 offset:37888
	ds_read_b128 v[226:229], v193 offset:38912
	ds_read_b128 v[230:233], v193 offset:39936
	s_mov_b32 m0, s69
	v_lshl_add_u64 v[234:235], v[202:203], 0, s[12:13]
	global_load_lds_dwordx4 v[234:235], off
	v_lshl_add_u64 v[234:235], v[202:203], 0, s[86:87]
	s_mov_b32 m0, s76
	s_nop 0
	global_load_lds_dwordx4 v[234:235], off
	s_waitcnt vmcnt(8) lgkmcnt(0)
	s_barrier
	v_mfma_f32_16x16x32_bf16 v[142:145], v[114:117], v[186:189], v[142:145]
	v_mfma_f32_16x16x32_bf16 v[142:145], v[126:129], v[194:197], v[142:145]
	v_mfma_f32_16x16x32_bf16 v[138:141], v[130:133], v[186:189], v[138:141]
	v_mfma_f32_16x16x32_bf16 v[138:141], v[134:137], v[194:197], v[138:141]
	v_mfma_f32_16x16x32_bf16 v[110:113], v[114:117], v[198:201], v[110:113]
	v_mfma_f32_16x16x32_bf16 v[110:113], v[126:129], v[214:217], v[110:113]
	v_mfma_f32_16x16x32_bf16 v[106:109], v[130:133], v[198:201], v[106:109]
	v_mfma_f32_16x16x32_bf16 v[106:109], v[134:137], v[214:217], v[106:109]
	v_mfma_f32_16x16x32_bf16 v[94:97], v[114:117], v[218:221], v[94:97]
	v_mfma_f32_16x16x32_bf16 v[94:97], v[126:129], v[222:225], v[94:97]
	v_mfma_f32_16x16x32_bf16 v[90:93], v[130:133], v[218:221], v[90:93]
	v_mfma_f32_16x16x32_bf16 v[90:93], v[134:137], v[222:225], v[90:93]
	v_mfma_f32_16x16x32_bf16 v[78:81], v[114:117], v[226:229], v[78:81]
	v_mfma_f32_16x16x32_bf16 v[78:81], v[126:129], v[230:233], v[78:81]
	v_mfma_f32_16x16x32_bf16 v[74:77], v[130:133], v[226:229], v[74:77]
	v_mfma_f32_16x16x32_bf16 v[74:77], v[134:137], v[230:233], v[74:77]
	v_mfma_f32_16x16x32_bf16 v[122:125], v[146:149], v[186:189], v[122:125]
	v_mfma_f32_16x16x32_bf16 v[122:125], v[150:153], v[194:197], v[122:125]
	v_mfma_f32_16x16x32_bf16 v[118:121], v[158:161], v[186:189], v[118:121]
	v_mfma_f32_16x16x32_bf16 v[118:121], v[182:185], v[194:197], v[118:121]
	v_mfma_f32_16x16x32_bf16 v[102:105], v[146:149], v[198:201], v[102:105]
	v_mfma_f32_16x16x32_bf16 v[102:105], v[150:153], v[214:217], v[102:105]
	v_mfma_f32_16x16x32_bf16 v[98:101], v[158:161], v[198:201], v[98:101]
	v_mfma_f32_16x16x32_bf16 v[98:101], v[182:185], v[214:217], v[98:101]
	v_mfma_f32_16x16x32_bf16 v[86:89], v[146:149], v[218:221], v[86:89]
	v_mfma_f32_16x16x32_bf16 v[86:89], v[150:153], v[222:225], v[86:89]
	v_mfma_f32_16x16x32_bf16 v[82:85], v[158:161], v[218:221], v[82:85]
	v_mfma_f32_16x16x32_bf16 v[82:85], v[182:185], v[222:225], v[82:85]
	v_mfma_f32_16x16x32_bf16 v[70:73], v[146:149], v[226:229], v[70:73]
	v_mfma_f32_16x16x32_bf16 v[70:73], v[150:153], v[230:233], v[70:73]
	v_mfma_f32_16x16x32_bf16 v[66:69], v[158:161], v[226:229], v[66:69]
	v_mfma_f32_16x16x32_bf16 v[66:69], v[182:185], v[230:233], v[66:69]
	s_barrier
	ds_read_b128 v[186:189], v193 offset:49152
	ds_read_b128 v[194:197], v193 offset:50176
	ds_read_b128 v[198:201], v193 offset:51200
	ds_read_b128 v[214:217], v193 offset:52224
	ds_read_b128 v[218:221], v193 offset:53248
	ds_read_b128 v[222:225], v193 offset:54272
	ds_read_b128 v[226:229], v193 offset:55296
	ds_read_b128 v[230:233], v193 offset:56320
	s_add_i32 s20, s20, s46
	s_mov_b32 m0, s20
	v_lshl_add_u64 v[234:235], v[162:163], 0, s[34:35]
	global_load_lds_dwordx4 v[234:235], off
	v_lshl_add_u64 v[234:235], v[162:163], 0, s[96:97]
	s_add_i32 m0, s20, 0x2000
	s_add_i32 s20, s21, s46
	global_load_lds_dwordx4 v[234:235], off
	v_lshl_add_u64 v[234:235], v[162:163], 0, vcc
	s_mov_b32 m0, s20
	v_lshl_add_u64 v[162:163], v[162:163], 0, s[0:1]
	global_load_lds_dwordx4 v[234:235], off
	s_add_i32 m0, s20, 0x2000
	s_nop 0
	global_load_lds_dwordx4 v[162:163], off
	v_lshl_add_u64 v[162:163], v[202:203], 0, s[34:35]
	s_mov_b32 m0, s77
	s_nop 0
	global_load_lds_dwordx4 v[162:163], off
	v_lshl_add_u64 v[162:163], v[202:203], 0, s[96:97]
	s_mov_b32 m0, s78
	s_nop 0
	global_load_lds_dwordx4 v[162:163], off
	s_waitcnt vmcnt(8) lgkmcnt(0)
	s_barrier
	v_mfma_f32_16x16x32_bf16 v[62:65], v[114:117], v[186:189], v[62:65]
	v_mfma_f32_16x16x32_bf16 v[62:65], v[126:129], v[194:197], v[62:65]
	v_mfma_f32_16x16x32_bf16 v[58:61], v[130:133], v[186:189], v[58:61]
	v_mfma_f32_16x16x32_bf16 v[58:61], v[134:137], v[194:197], v[58:61]
	v_mfma_f32_16x16x32_bf16 v[46:49], v[114:117], v[198:201], v[46:49]
	v_mfma_f32_16x16x32_bf16 v[46:49], v[126:129], v[214:217], v[46:49]
	v_mfma_f32_16x16x32_bf16 v[42:45], v[130:133], v[198:201], v[42:45]
	v_mfma_f32_16x16x32_bf16 v[42:45], v[134:137], v[214:217], v[42:45]
	v_mfma_f32_16x16x32_bf16 v[30:33], v[114:117], v[218:221], v[30:33]
	v_mfma_f32_16x16x32_bf16 v[30:33], v[126:129], v[222:225], v[30:33]
	v_mfma_f32_16x16x32_bf16 v[26:29], v[130:133], v[218:221], v[26:29]
	v_mfma_f32_16x16x32_bf16 v[26:29], v[134:137], v[222:225], v[26:29]
	v_mfma_f32_16x16x32_bf16 v[14:17], v[114:117], v[226:229], v[14:17]
	v_mfma_f32_16x16x32_bf16 v[14:17], v[126:129], v[230:233], v[14:17]
	v_mfma_f32_16x16x32_bf16 v[10:13], v[130:133], v[226:229], v[10:13]
	v_mfma_f32_16x16x32_bf16 v[10:13], v[134:137], v[230:233], v[10:13]
	s_add_i32 s84, s84, 2
	s_add_u32 s56, s56, 0x100
	s_addc_u32 s57, s57, 0
	s_add_u32 s62, s62, 0x100
	s_addc_u32 s63, s63, 0
	s_cmp_gt_u32 s84, 41
	v_mfma_f32_16x16x32_bf16 v[54:57], v[146:149], v[186:189], v[54:57]
	v_mfma_f32_16x16x32_bf16 v[54:57], v[150:153], v[194:197], v[54:57]
	v_mfma_f32_16x16x32_bf16 v[50:53], v[158:161], v[186:189], v[50:53]
	v_mfma_f32_16x16x32_bf16 v[50:53], v[182:185], v[194:197], v[50:53]
	v_mfma_f32_16x16x32_bf16 v[38:41], v[146:149], v[198:201], v[38:41]
	v_mfma_f32_16x16x32_bf16 v[38:41], v[150:153], v[214:217], v[38:41]
	v_mfma_f32_16x16x32_bf16 v[34:37], v[158:161], v[198:201], v[34:37]
	v_mfma_f32_16x16x32_bf16 v[34:37], v[182:185], v[214:217], v[34:37]
	v_mfma_f32_16x16x32_bf16 v[22:25], v[146:149], v[218:221], v[22:25]
	v_mfma_f32_16x16x32_bf16 v[22:25], v[150:153], v[222:225], v[22:25]
	v_mfma_f32_16x16x32_bf16 v[18:21], v[158:161], v[218:221], v[18:21]
	v_mfma_f32_16x16x32_bf16 v[18:21], v[182:185], v[222:225], v[18:21]
	v_mfma_f32_16x16x32_bf16 v[6:9], v[146:149], v[226:229], v[6:9]
	v_mfma_f32_16x16x32_bf16 v[6:9], v[150:153], v[230:233], v[6:9]
	v_mfma_f32_16x16x32_bf16 v[2:5], v[158:161], v[226:229], v[2:5]
	v_mfma_f32_16x16x32_bf16 v[2:5], v[182:185], v[230:233], v[2:5]
	s_barrier
	s_cbranch_scc0 .LBB0_446
	s_setprio 0
	s_and_b64 vcc, exec, s[40:41]
	s_cbranch_vccz .LBB0_449
	s_barrier

.LBB0_488:
	s_add_i32 s22, 0, 0x10000
	v_add_u32_e32 v143, s22, v139
	s_add_i32 s23, 0, 0x14000
	ds_read_b128 v[134:137], v143
	ds_read_b128 v[144:147], v143 offset:1024
	ds_read_b128 v[148:151], v143 offset:2048
	ds_read_b128 v[152:155], v143 offset:3072
	v_add_u32_e32 v143, s23, v139
	ds_read_b128 v[156:159], v143
	ds_read_b128 v[160:163], v143 offset:1024
	ds_read_b128 v[182:185], v143 offset:2048
	ds_read_b128 v[186:189], v143 offset:3072
	ds_read_b128 v[190:193], v142
	ds_read_b128 v[194:197], v142 offset:1024
	ds_read_b128 v[198:201], v142 offset:2048
	ds_read_b128 v[214:217], v142 offset:3072
	ds_read_b128 v[218:221], v142 offset:4096
	ds_read_b128 v[222:225], v142 offset:5120
	ds_read_b128 v[226:229], v142 offset:6144
	ds_read_b128 v[230:233], v142 offset:7168
	s_add_u32 s20, s68, 0xfffc0080
	s_addc_u32 s21, s69, -1
	s_cmp_eq_u32 s97, 12
	s_cselect_b32 s77, s57, s21
	s_cselect_b32 s76, s86, s20
	s_cselect_b32 s21, s51, s96
	s_cselect_b32 s20, s87, s91
	s_add_i32 m0, s43, 0xc000
	v_lshl_add_u64 v[202:203], s[68:69], 0, v[132:133]
	global_load_lds_dwordx4 v[202:203], off
	v_lshl_add_u64 v[202:203], v[202:203], 0, s[72:73]
	s_add_i32 m0, s43, 0xe000
	s_nop 0
	global_load_lds_dwordx4 v[202:203], off
	s_waitcnt vmcnt(8) lgkmcnt(0)
	s_barrier
	v_mfma_f32_16x16x32_bf16 v[126:129], v[134:137], v[190:193], v[126:129]
	v_mfma_f32_16x16x32_bf16 v[126:129], v[144:147], v[194:197], v[126:129]
	v_mfma_f32_16x16x32_bf16 v[114:117], v[148:151], v[190:193], v[114:117]
	v_mfma_f32_16x16x32_bf16 v[114:117], v[152:155], v[194:197], v[114:117]
	v_mfma_f32_16x16x32_bf16 v[110:113], v[134:137], v[198:201], v[110:113]
	v_mfma_f32_16x16x32_bf16 v[110:113], v[144:147], v[214:217], v[110:113]
	v_mfma_f32_16x16x32_bf16 v[98:101], v[148:151], v[198:201], v[98:101]
	v_mfma_f32_16x16x32_bf16 v[98:101], v[152:155], v[214:217], v[98:101]
	v_mfma_f32_16x16x32_bf16 v[94:97], v[134:137], v[218:221], v[94:97]
	v_mfma_f32_16x16x32_bf16 v[94:97], v[144:147], v[222:225], v[94:97]
	v_mfma_f32_16x16x32_bf16 v[82:85], v[148:151], v[218:221], v[82:85]
	v_mfma_f32_16x16x32_bf16 v[82:85], v[152:155], v[222:225], v[82:85]
	v_mfma_f32_16x16x32_bf16 v[78:81], v[134:137], v[226:229], v[78:81]
	v_mfma_f32_16x16x32_bf16 v[78:81], v[144:147], v[230:233], v[78:81]
	v_mfma_f32_16x16x32_bf16 v[66:69], v[148:151], v[226:229], v[66:69]
	v_mfma_f32_16x16x32_bf16 v[66:69], v[152:155], v[230:233], v[66:69]
	v_mfma_f32_16x16x32_bf16 v[122:125], v[156:159], v[190:193], v[122:125]
	v_mfma_f32_16x16x32_bf16 v[122:125], v[160:163], v[194:197], v[122:125]
	v_mfma_f32_16x16x32_bf16 v[118:121], v[182:185], v[190:193], v[118:121]
	v_mfma_f32_16x16x32_bf16 v[118:121], v[186:189], v[194:197], v[118:121]
	v_mfma_f32_16x16x32_bf16 v[106:109], v[156:159], v[198:201], v[106:109]
	v_mfma_f32_16x16x32_bf16 v[106:109], v[160:163], v[214:217], v[106:109]
	v_mfma_f32_16x16x32_bf16 v[102:105], v[182:185], v[198:201], v[102:105]
	v_mfma_f32_16x16x32_bf16 v[102:105], v[186:189], v[214:217], v[102:105]
	v_mfma_f32_16x16x32_bf16 v[90:93], v[156:159], v[218:221], v[90:93]
	v_mfma_f32_16x16x32_bf16 v[90:93], v[160:163], v[222:225], v[90:93]
	v_mfma_f32_16x16x32_bf16 v[86:89], v[182:185], v[218:221], v[86:89]
	v_mfma_f32_16x16x32_bf16 v[86:89], v[186:189], v[222:225], v[86:89]
	v_mfma_f32_16x16x32_bf16 v[74:77], v[156:159], v[226:229], v[74:77]
	v_mfma_f32_16x16x32_bf16 v[74:77], v[160:163], v[230:233], v[74:77]
	v_mfma_f32_16x16x32_bf16 v[70:73], v[182:185], v[226:229], v[70:73]
	v_mfma_f32_16x16x32_bf16 v[70:73], v[186:189], v[230:233], v[70:73]
	s_barrier
	ds_read_b128 v[190:193], v142 offset:16384
	ds_read_b128 v[194:197], v142 offset:17408
	ds_read_b128 v[198:201], v142 offset:18432
	ds_read_b128 v[214:217], v142 offset:19456
	ds_read_b128 v[218:221], v142 offset:20480
	ds_read_b128 v[222:225], v142 offset:21504
	ds_read_b128 v[226:229], v142 offset:22528
	ds_read_b128 v[230:233], v142 offset:23552
	v_lshl_add_u64 v[202:203], s[20:21], 0, v[0:1]
	s_add_i32 s20, s22, s14
	s_mov_b32 m0, s20
	s_nop 0
	s_nop 0
	global_load_lds_dwordx4 v[202:203], off
	v_lshl_add_u64 v[234:235], v[202:203], 0, s[72:73]
	s_add_i32 m0, s20, 0x2000
	s_add_i32 s20, s23, s14
	global_load_lds_dwordx4 v[234:235], off
	v_lshl_add_u64 v[234:235], v[202:203], 0, s[28:29]
	s_mov_b32 m0, s20
	s_nop 0
	global_load_lds_dwordx4 v[234:235], off
	v_lshl_add_u64 v[234:235], v[202:203], 0, s[82:83]
	s_add_i32 m0, s20, 0x2000
	s_nop 0
	global_load_lds_dwordx4 v[234:235], off
	v_lshl_add_u64 v[234:235], s[76:77], 0, v[130:131]
	s_mov_b32 m0, s43
	v_lshl_add_u64 v[236:237], v[234:235], 0, s[72:73]
	global_load_lds_dwordx4 v[234:235], off
	s_mov_b32 m0, s46
	s_nop 0
	global_load_lds_dwordx4 v[236:237], off
	s_waitcnt vmcnt(8) lgkmcnt(0)
	s_barrier
	v_mfma_f32_16x16x32_bf16 v[62:65], v[134:137], v[190:193], v[62:65]
	v_mfma_f32_16x16x32_bf16 v[62:65], v[144:147], v[194:197], v[62:65]
	v_mfma_f32_16x16x32_bf16 v[50:53], v[148:151], v[190:193], v[50:53]
	v_mfma_f32_16x16x32_bf16 v[50:53], v[152:155], v[194:197], v[50:53]
	v_mfma_f32_16x16x32_bf16 v[46:49], v[134:137], v[198:201], v[46:49]
	v_mfma_f32_16x16x32_bf16 v[46:49], v[144:147], v[214:217], v[46:49]
	v_mfma_f32_16x16x32_bf16 v[34:37], v[148:151], v[198:201], v[34:37]
	v_mfma_f32_16x16x32_bf16 v[34:37], v[152:155], v[214:217], v[34:37]
	v_mfma_f32_16x16x32_bf16 v[30:33], v[134:137], v[218:221], v[30:33]
	v_mfma_f32_16x16x32_bf16 v[30:33], v[144:147], v[222:225], v[30:33]
	v_mfma_f32_16x16x32_bf16 v[18:21], v[148:151], v[218:221], v[18:21]
	v_mfma_f32_16x16x32_bf16 v[18:21], v[152:155], v[222:225], v[18:21]
	v_mfma_f32_16x16x32_bf16 v[14:17], v[134:137], v[226:229], v[14:17]
	v_mfma_f32_16x16x32_bf16 v[14:17], v[144:147], v[230:233], v[14:17]
	v_mfma_f32_16x16x32_bf16 v[6:9], v[148:151], v[226:229], v[6:9]
	v_mfma_f32_16x16x32_bf16 v[6:9], v[152:155], v[230:233], v[6:9]
	v_mfma_f32_16x16x32_bf16 v[58:61], v[156:159], v[190:193], v[58:61]
	v_mfma_f32_16x16x32_bf16 v[58:61], v[160:163], v[194:197], v[58:61]
	v_mfma_f32_16x16x32_bf16 v[54:57], v[182:185], v[190:193], v[54:57]
	v_mfma_f32_16x16x32_bf16 v[54:57], v[186:189], v[194:197], v[54:57]
	v_mfma_f32_16x16x32_bf16 v[42:45], v[156:159], v[198:201], v[42:45]
	v_mfma_f32_16x16x32_bf16 v[42:45], v[160:163], v[214:217], v[42:45]
	v_mfma_f32_16x16x32_bf16 v[38:41], v[182:185], v[198:201], v[38:41]
	v_mfma_f32_16x16x32_bf16 v[38:41], v[186:189], v[214:217], v[38:41]
	v_mfma_f32_16x16x32_bf16 v[26:29], v[156:159], v[218:221], v[26:29]
	v_mfma_f32_16x16x32_bf16 v[26:29], v[160:163], v[222:225], v[26:29]
	v_mfma_f32_16x16x32_bf16 v[22:25], v[182:185], v[218:221], v[22:25]
	v_mfma_f32_16x16x32_bf16 v[22:25], v[186:189], v[222:225], v[22:25]
	v_mfma_f32_16x16x32_bf16 v[10:13], v[156:159], v[226:229], v[10:13]
	v_mfma_f32_16x16x32_bf16 v[10:13], v[160:163], v[230:233], v[10:13]
	v_mfma_f32_16x16x32_bf16 v[2:5], v[182:185], v[226:229], v[2:5]
	v_mfma_f32_16x16x32_bf16 v[2:5], v[186:189], v[230:233], v[2:5]
	s_barrier
	s_add_i32 s20, 0, 0x18000
	v_add_u32_e32 v143, s20, v139
	s_add_i32 s21, 0, 0x1c000
	ds_read_b128 v[134:137], v143
	ds_read_b128 v[144:147], v143 offset:1024
	ds_read_b128 v[148:151], v143 offset:2048
	ds_read_b128 v[152:155], v143 offset:3072
	v_add_u32_e32 v143, s21, v139
	ds_read_b128 v[156:159], v143
	ds_read_b128 v[160:163], v143 offset:1024
	ds_read_b128 v[182:185], v143 offset:2048
	ds_read_b128 v[186:189], v143 offset:3072
	ds_read_b128 v[190:193], v142 offset:32768
	ds_read_b128 v[194:197], v142 offset:33792
	ds_read_b128 v[198:201], v142 offset:34816
	ds_read_b128 v[214:217], v142 offset:35840
	ds_read_b128 v[218:221], v142 offset:36864
	ds_read_b128 v[222:225], v142 offset:37888
	ds_read_b128 v[226:229], v142 offset:38912
	ds_read_b128 v[230:233], v142 offset:39936
	s_mov_b32 m0, s47
	v_lshl_add_u64 v[236:237], v[234:235], 0, s[28:29]
	global_load_lds_dwordx4 v[236:237], off
	v_lshl_add_u64 v[236:237], v[234:235], 0, s[82:83]
	s_mov_b32 m0, s78
	s_nop 0
	global_load_lds_dwordx4 v[236:237], off
	s_waitcnt vmcnt(8) lgkmcnt(0)
	s_barrier
	v_mfma_f32_16x16x32_bf16 v[126:129], v[134:137], v[190:193], v[126:129]
	v_mfma_f32_16x16x32_bf16 v[126:129], v[144:147], v[194:197], v[126:129]
	v_mfma_f32_16x16x32_bf16 v[114:117], v[148:151], v[190:193], v[114:117]
	v_mfma_f32_16x16x32_bf16 v[114:117], v[152:155], v[194:197], v[114:117]
	v_mfma_f32_16x16x32_bf16 v[110:113], v[134:137], v[198:201], v[110:113]
	v_mfma_f32_16x16x32_bf16 v[110:113], v[144:147], v[214:217], v[110:113]
	v_mfma_f32_16x16x32_bf16 v[98:101], v[148:151], v[198:201], v[98:101]
	v_mfma_f32_16x16x32_bf16 v[98:101], v[152:155], v[214:217], v[98:101]
	v_mfma_f32_16x16x32_bf16 v[94:97], v[134:137], v[218:221], v[94:97]
	v_mfma_f32_16x16x32_bf16 v[94:97], v[144:147], v[222:225], v[94:97]
	v_mfma_f32_16x16x32_bf16 v[82:85], v[148:151], v[218:221], v[82:85]
	v_mfma_f32_16x16x32_bf16 v[82:85], v[152:155], v[222:225], v[82:85]
	v_mfma_f32_16x16x32_bf16 v[78:81], v[134:137], v[226:229], v[78:81]
	v_mfma_f32_16x16x32_bf16 v[78:81], v[144:147], v[230:233], v[78:81]
	v_mfma_f32_16x16x32_bf16 v[66:69], v[148:151], v[226:229], v[66:69]
	v_mfma_f32_16x16x32_bf16 v[66:69], v[152:155], v[230:233], v[66:69]
	v_mfma_f32_16x16x32_bf16 v[122:125], v[156:159], v[190:193], v[122:125]
	v_mfma_f32_16x16x32_bf16 v[122:125], v[160:163], v[194:197], v[122:125]
	v_mfma_f32_16x16x32_bf16 v[118:121], v[182:185], v[190:193], v[118:121]
	v_mfma_f32_16x16x32_bf16 v[118:121], v[186:189], v[194:197], v[118:121]
	v_mfma_f32_16x16x32_bf16 v[106:109], v[156:159], v[198:201], v[106:109]
	v_mfma_f32_16x16x32_bf16 v[106:109], v[160:163], v[214:217], v[106:109]
	v_mfma_f32_16x16x32_bf16 v[102:105], v[182:185], v[198:201], v[102:105]
	v_mfma_f32_16x16x32_bf16 v[102:105], v[186:189], v[214:217], v[102:105]
	v_mfma_f32_16x16x32_bf16 v[90:93], v[156:159], v[218:221], v[90:93]
	v_mfma_f32_16x16x32_bf16 v[90:93], v[160:163], v[222:225], v[90:93]
	v_mfma_f32_16x16x32_bf16 v[86:89], v[182:185], v[218:221], v[86:89]
	v_mfma_f32_16x16x32_bf16 v[86:89], v[186:189], v[222:225], v[86:89]
	v_mfma_f32_16x16x32_bf16 v[74:77], v[156:159], v[226:229], v[74:77]
	v_mfma_f32_16x16x32_bf16 v[74:77], v[160:163], v[230:233], v[74:77]
	v_mfma_f32_16x16x32_bf16 v[70:73], v[182:185], v[226:229], v[70:73]
	v_mfma_f32_16x16x32_bf16 v[70:73], v[186:189], v[230:233], v[70:73]
	s_barrier
	ds_read_b128 v[190:193], v142 offset:49152
	ds_read_b128 v[194:197], v142 offset:50176
	ds_read_b128 v[198:201], v142 offset:51200
	ds_read_b128 v[214:217], v142 offset:52224
	ds_read_b128 v[218:221], v142 offset:53248
	ds_read_b128 v[222:225], v142 offset:54272
	ds_read_b128 v[226:229], v142 offset:55296
	ds_read_b128 v[230:233], v142 offset:56320
	s_add_i32 s20, s20, s14
	s_mov_b32 m0, s20
	v_lshl_add_u64 v[236:237], v[202:203], 0, s[34:35]
	global_load_lds_dwordx4 v[236:237], off
	v_lshl_add_u64 v[236:237], v[202:203], 0, s[38:39]
	s_add_i32 m0, s20, 0x2000
	s_add_i32 s20, s21, s14
	global_load_lds_dwordx4 v[236:237], off
	v_lshl_add_u64 v[236:237], v[202:203], 0, s[44:45]
	s_mov_b32 m0, s20
	v_lshl_add_u64 v[202:203], v[202:203], 0, s[10:11]
	global_load_lds_dwordx4 v[236:237], off
	s_add_i32 m0, s20, 0x2000
	s_nop 0
	global_load_lds_dwordx4 v[202:203], off
	v_lshl_add_u64 v[202:203], v[234:235], 0, s[34:35]
	s_mov_b32 m0, s79
	s_nop 0
	global_load_lds_dwordx4 v[202:203], off
	v_lshl_add_u64 v[202:203], v[234:235], 0, s[38:39]
	s_mov_b32 m0, s88
	s_nop 0
	global_load_lds_dwordx4 v[202:203], off
	s_waitcnt vmcnt(8) lgkmcnt(0)
	s_barrier
	v_mfma_f32_16x16x32_bf16 v[62:65], v[134:137], v[190:193], v[62:65]
	v_mfma_f32_16x16x32_bf16 v[62:65], v[144:147], v[194:197], v[62:65]
	v_mfma_f32_16x16x32_bf16 v[50:53], v[148:151], v[190:193], v[50:53]
	v_mfma_f32_16x16x32_bf16 v[50:53], v[152:155], v[194:197], v[50:53]
	v_mfma_f32_16x16x32_bf16 v[46:49], v[134:137], v[198:201], v[46:49]
	v_mfma_f32_16x16x32_bf16 v[46:49], v[144:147], v[214:217], v[46:49]
	v_mfma_f32_16x16x32_bf16 v[34:37], v[148:151], v[198:201], v[34:37]
	v_mfma_f32_16x16x32_bf16 v[34:37], v[152:155], v[214:217], v[34:37]
	v_mfma_f32_16x16x32_bf16 v[30:33], v[134:137], v[218:221], v[30:33]
	v_mfma_f32_16x16x32_bf16 v[30:33], v[144:147], v[222:225], v[30:33]
	v_mfma_f32_16x16x32_bf16 v[18:21], v[148:151], v[218:221], v[18:21]
	v_mfma_f32_16x16x32_bf16 v[18:21], v[152:155], v[222:225], v[18:21]
	v_mfma_f32_16x16x32_bf16 v[14:17], v[134:137], v[226:229], v[14:17]
	v_mfma_f32_16x16x32_bf16 v[14:17], v[144:147], v[230:233], v[14:17]
	v_mfma_f32_16x16x32_bf16 v[6:9], v[148:151], v[226:229], v[6:9]
	v_mfma_f32_16x16x32_bf16 v[6:9], v[152:155], v[230:233], v[6:9]
	s_add_i32 s97, s97, 2
	s_add_u32 s68, s68, 0x100
	s_addc_u32 s69, s69, 0
	s_add_u32 s91, s91, 0x100
	s_addc_u32 s96, s96, 0
	s_cmp_gt_u32 s97, 13
	v_mfma_f32_16x16x32_bf16 v[58:61], v[156:159], v[190:193], v[58:61]
	v_mfma_f32_16x16x32_bf16 v[58:61], v[160:163], v[194:197], v[58:61]
	v_mfma_f32_16x16x32_bf16 v[54:57], v[182:185], v[190:193], v[54:57]
	v_mfma_f32_16x16x32_bf16 v[54:57], v[186:189], v[194:197], v[54:57]
	v_mfma_f32_16x16x32_bf16 v[42:45], v[156:159], v[198:201], v[42:45]
	v_mfma_f32_16x16x32_bf16 v[42:45], v[160:163], v[214:217], v[42:45]
	v_mfma_f32_16x16x32_bf16 v[38:41], v[182:185], v[198:201], v[38:41]
	v_mfma_f32_16x16x32_bf16 v[38:41], v[186:189], v[214:217], v[38:41]
	v_mfma_f32_16x16x32_bf16 v[26:29], v[156:159], v[218:221], v[26:29]
	v_mfma_f32_16x16x32_bf16 v[26:29], v[160:163], v[222:225], v[26:29]
	v_mfma_f32_16x16x32_bf16 v[22:25], v[182:185], v[218:221], v[22:25]
	v_mfma_f32_16x16x32_bf16 v[22:25], v[186:189], v[222:225], v[22:25]
	v_mfma_f32_16x16x32_bf16 v[10:13], v[156:159], v[226:229], v[10:13]
	v_mfma_f32_16x16x32_bf16 v[10:13], v[160:163], v[230:233], v[10:13]
	v_mfma_f32_16x16x32_bf16 v[2:5], v[182:185], v[226:229], v[2:5]
	v_mfma_f32_16x16x32_bf16 v[2:5], v[186:189], v[230:233], v[2:5]
	s_barrier
	s_cbranch_scc0 .LBB0_488
	s_setprio 0
	s_and_b64 vcc, exec, s[48:49]
	s_cbranch_vccz .LBB0_491
	s_barrier

.LBB0_562:
	s_add_u32 s20, s62, s68
	s_addc_u32 s21, s63, s69
	s_add_u32 s20, s20, 0x100
	s_addc_u32 s21, s21, 0
	s_add_u32 s22, s97, s68
	s_addc_u32 s23, vcc_lo, s69
	s_cmpk_eq_i32 s68, 0x700
	s_cselect_b32 s77, s51, s21
	s_cselect_b32 s76, s86, s20
	s_cselect_b32 s21, s49, s23
	s_cselect_b32 s20, s87, s22
	s_add_i32 s22, 0, 0x10000
	v_add_u32_e32 v0, s22, v215
	s_add_i32 s23, 0, 0x14000
	ds_read_b128 v[118:121], v0
	ds_read_b128 v[122:125], v0 offset:1024
	ds_read_b128 v[132:135], v0 offset:2048
	ds_read_b128 v[148:151], v0 offset:3072
	v_add_u32_e32 v0, s23, v215
	ds_read_b128 v[152:155], v0
	ds_read_b128 v[156:159], v0 offset:1024
	ds_read_b128 v[160:163], v0 offset:2048
	ds_read_b128 v[188:191], v0 offset:3072
	v_lshl_add_u64 v[2:3], v[116:117], 0, s[68:69]
	v_lshl_add_u64 v[126:127], v[2:3], 0, s[44:45]
	s_add_i32 m0, s47, 0xc000
	ds_read_b128 v[192:195], v218
	ds_read_b128 v[196:199], v218 offset:1024
	ds_read_b128 v[200:203], v218 offset:2048
	ds_read_b128 v[220:223], v218 offset:3072
	ds_read_b128 v[224:227], v218 offset:4096
	ds_read_b128 v[228:231], v218 offset:5120
	ds_read_b128 v[232:235], v218 offset:6144
	ds_read_b128 v[236:239], v218 offset:7168
	global_load_lds_dwordx4 v[126:127], off
	v_lshl_add_u64 v[2:3], v[2:3], 0, s[10:11]
	s_add_i32 m0, s47, 0xe000
	s_nop 0
	global_load_lds_dwordx4 v[2:3], off
	s_waitcnt vmcnt(8) lgkmcnt(0)
	s_barrier
	v_mfma_f32_16x16x32_bf16 v[144:147], v[118:121], v[192:195], v[144:147]
	v_mfma_f32_16x16x32_bf16 v[144:147], v[122:125], v[196:199], v[144:147]
	v_mfma_f32_16x16x32_bf16 v[140:143], v[132:135], v[192:195], v[140:143]
	v_mfma_f32_16x16x32_bf16 v[140:143], v[148:151], v[196:199], v[140:143]
	v_mfma_f32_16x16x32_bf16 v[112:115], v[118:121], v[200:203], v[112:115]
	v_mfma_f32_16x16x32_bf16 v[112:115], v[122:125], v[220:223], v[112:115]
	v_mfma_f32_16x16x32_bf16 v[108:111], v[132:135], v[200:203], v[108:111]
	v_mfma_f32_16x16x32_bf16 v[108:111], v[148:151], v[220:223], v[108:111]
	v_mfma_f32_16x16x32_bf16 v[96:99], v[118:121], v[224:227], v[96:99]
	v_mfma_f32_16x16x32_bf16 v[96:99], v[122:125], v[228:231], v[96:99]
	v_mfma_f32_16x16x32_bf16 v[92:95], v[132:135], v[224:227], v[92:95]
	v_mfma_f32_16x16x32_bf16 v[92:95], v[148:151], v[228:231], v[92:95]
	v_mfma_f32_16x16x32_bf16 v[80:83], v[118:121], v[232:235], v[80:83]
	v_mfma_f32_16x16x32_bf16 v[80:83], v[122:125], v[236:239], v[80:83]
	v_mfma_f32_16x16x32_bf16 v[76:79], v[132:135], v[232:235], v[76:79]
	v_mfma_f32_16x16x32_bf16 v[76:79], v[148:151], v[236:239], v[76:79]
	v_mfma_f32_16x16x32_bf16 v[136:139], v[152:155], v[192:195], v[136:139]
	v_mfma_f32_16x16x32_bf16 v[136:139], v[156:159], v[196:199], v[136:139]
	v_mfma_f32_16x16x32_bf16 v[126:129], v[160:163], v[192:195], v[128:131]
	v_mfma_f32_16x16x32_bf16 v[126:129], v[188:191], v[196:199], v[126:129]
	v_mfma_f32_16x16x32_bf16 v[104:107], v[152:155], v[200:203], v[104:107]
	v_mfma_f32_16x16x32_bf16 v[104:107], v[156:159], v[220:223], v[104:107]
	v_mfma_f32_16x16x32_bf16 v[100:103], v[160:163], v[200:203], v[100:103]
	v_mfma_f32_16x16x32_bf16 v[100:103], v[188:191], v[220:223], v[100:103]
	v_mfma_f32_16x16x32_bf16 v[88:91], v[152:155], v[224:227], v[88:91]
	v_mfma_f32_16x16x32_bf16 v[88:91], v[156:159], v[228:231], v[88:91]
	v_mfma_f32_16x16x32_bf16 v[84:87], v[160:163], v[224:227], v[84:87]
	v_mfma_f32_16x16x32_bf16 v[84:87], v[188:191], v[228:231], v[84:87]
	v_mfma_f32_16x16x32_bf16 v[72:75], v[152:155], v[232:235], v[72:75]
	v_mfma_f32_16x16x32_bf16 v[72:75], v[156:159], v[236:239], v[72:75]
	v_mfma_f32_16x16x32_bf16 v[68:71], v[160:163], v[232:235], v[68:71]
	v_mfma_f32_16x16x32_bf16 v[68:71], v[188:191], v[236:239], v[68:71]
	s_barrier
	v_lshl_add_u64 v[240:241], s[20:21], 0, v[182:183]
	s_add_i32 s20, s22, s14
	s_mov_b32 m0, s20
	ds_read_b128 v[192:195], v218 offset:16384
	ds_read_b128 v[196:199], v218 offset:17408
	ds_read_b128 v[200:203], v218 offset:18432
	ds_read_b128 v[220:223], v218 offset:19456
	ds_read_b128 v[224:227], v218 offset:20480
	ds_read_b128 v[228:231], v218 offset:21504
	ds_read_b128 v[232:235], v218 offset:22528
	ds_read_b128 v[236:239], v218 offset:23552
	global_load_lds_dwordx4 v[240:241], off
	v_lshl_add_u64 v[2:3], v[240:241], 0, s[72:73]
	s_add_i32 m0, s20, 0x2000
	s_add_i32 s20, s23, s14
	global_load_lds_dwordx4 v[2:3], off
	v_lshl_add_u64 v[2:3], v[240:241], 0, s[28:29]
	s_mov_b32 m0, s20
	v_lshl_add_u64 v[242:243], s[76:77], 0, v[184:185]
	global_load_lds_dwordx4 v[2:3], off
	v_lshl_add_u64 v[2:3], v[240:241], 0, s[82:83]
	s_add_i32 m0, s20, 0x2000
	s_nop 0
	global_load_lds_dwordx4 v[2:3], off
	s_mov_b32 m0, s47
	v_lshl_add_u64 v[2:3], v[242:243], 0, s[72:73]
	global_load_lds_dwordx4 v[242:243], off
	s_mov_b32 m0, s79
	s_nop 0
	global_load_lds_dwordx4 v[2:3], off
	s_waitcnt vmcnt(8) lgkmcnt(0)
	s_barrier
	v_mfma_f32_16x16x32_bf16 v[64:67], v[118:121], v[192:195], v[64:67]
	v_mfma_f32_16x16x32_bf16 v[64:67], v[122:125], v[196:199], v[64:67]
	v_mfma_f32_16x16x32_bf16 v[60:63], v[132:135], v[192:195], v[60:63]
	v_mfma_f32_16x16x32_bf16 v[60:63], v[148:151], v[196:199], v[60:63]
	v_mfma_f32_16x16x32_bf16 v[48:51], v[118:121], v[200:203], v[48:51]
	v_mfma_f32_16x16x32_bf16 v[48:51], v[122:125], v[220:223], v[48:51]
	v_mfma_f32_16x16x32_bf16 v[44:47], v[132:135], v[200:203], v[44:47]
	v_mfma_f32_16x16x32_bf16 v[44:47], v[148:151], v[220:223], v[44:47]
	v_mfma_f32_16x16x32_bf16 v[32:35], v[118:121], v[224:227], v[32:35]
	v_mfma_f32_16x16x32_bf16 v[32:35], v[122:125], v[228:231], v[32:35]
	v_mfma_f32_16x16x32_bf16 v[28:31], v[132:135], v[224:227], v[28:31]
	v_mfma_f32_16x16x32_bf16 v[28:31], v[148:151], v[228:231], v[28:31]
	v_mfma_f32_16x16x32_bf16 v[16:19], v[118:121], v[232:235], v[16:19]
	v_mfma_f32_16x16x32_bf16 v[16:19], v[122:125], v[236:239], v[16:19]
	v_mfma_f32_16x16x32_bf16 v[12:15], v[132:135], v[232:235], v[12:15]
	v_mfma_f32_16x16x32_bf16 v[12:15], v[148:151], v[236:239], v[12:15]
	v_mfma_f32_16x16x32_bf16 v[56:59], v[152:155], v[192:195], v[56:59]
	v_mfma_f32_16x16x32_bf16 v[56:59], v[156:159], v[196:199], v[56:59]
	v_mfma_f32_16x16x32_bf16 v[52:55], v[160:163], v[192:195], v[52:55]
	v_mfma_f32_16x16x32_bf16 v[52:55], v[188:191], v[196:199], v[52:55]
	v_mfma_f32_16x16x32_bf16 v[40:43], v[152:155], v[200:203], v[40:43]
	v_mfma_f32_16x16x32_bf16 v[40:43], v[156:159], v[220:223], v[40:43]
	v_mfma_f32_16x16x32_bf16 v[36:39], v[160:163], v[200:203], v[36:39]
	v_mfma_f32_16x16x32_bf16 v[36:39], v[188:191], v[220:223], v[36:39]
	v_mfma_f32_16x16x32_bf16 v[24:27], v[152:155], v[224:227], v[24:27]
	v_mfma_f32_16x16x32_bf16 v[24:27], v[156:159], v[228:231], v[24:27]
	v_mfma_f32_16x16x32_bf16 v[20:23], v[160:163], v[224:227], v[20:23]
	v_mfma_f32_16x16x32_bf16 v[20:23], v[188:191], v[228:231], v[20:23]
	v_mfma_f32_16x16x32_bf16 v[8:11], v[152:155], v[232:235], v[8:11]
	v_mfma_f32_16x16x32_bf16 v[8:11], v[156:159], v[236:239], v[8:11]
	v_mfma_f32_16x16x32_bf16 v[2:5], v[160:163], v[232:235], v[4:7]
	v_mfma_f32_16x16x32_bf16 v[2:5], v[188:191], v[236:239], v[2:5]
	s_barrier
	s_add_i32 s20, 0, 0x18000
	v_add_u32_e32 v0, s20, v215
	s_add_i32 s21, 0, 0x1c000
	ds_read_b128 v[118:121], v0
	ds_read_b128 v[122:125], v0 offset:1024
	ds_read_b128 v[132:135], v0 offset:2048
	ds_read_b128 v[148:151], v0 offset:3072
	v_add_u32_e32 v0, s21, v215
	ds_read_b128 v[152:155], v0
	ds_read_b128 v[156:159], v0 offset:1024
	ds_read_b128 v[160:163], v0 offset:2048
	ds_read_b128 v[188:191], v0 offset:3072
	s_mov_b32 m0, s88
	v_lshl_add_u64 v[6:7], v[242:243], 0, s[28:29]
	ds_read_b128 v[192:195], v218 offset:32768
	ds_read_b128 v[196:199], v218 offset:33792
	ds_read_b128 v[200:203], v218 offset:34816
	ds_read_b128 v[220:223], v218 offset:35840
	ds_read_b128 v[224:227], v218 offset:36864
	ds_read_b128 v[228:231], v218 offset:37888
	ds_read_b128 v[232:235], v218 offset:38912
	ds_read_b128 v[236:239], v218 offset:39936
	global_load_lds_dwordx4 v[6:7], off
	v_lshl_add_u64 v[6:7], v[242:243], 0, s[82:83]
	s_mov_b32 m0, s89
	s_nop 0
	global_load_lds_dwordx4 v[6:7], off
	s_waitcnt vmcnt(8) lgkmcnt(0)
	s_barrier
	v_mfma_f32_16x16x32_bf16 v[144:147], v[118:121], v[192:195], v[144:147]
	v_mfma_f32_16x16x32_bf16 v[144:147], v[122:125], v[196:199], v[144:147]
	v_mfma_f32_16x16x32_bf16 v[140:143], v[132:135], v[192:195], v[140:143]
	v_mfma_f32_16x16x32_bf16 v[140:143], v[148:151], v[196:199], v[140:143]
	v_mfma_f32_16x16x32_bf16 v[112:115], v[118:121], v[200:203], v[112:115]
	v_mfma_f32_16x16x32_bf16 v[112:115], v[122:125], v[220:223], v[112:115]
	v_mfma_f32_16x16x32_bf16 v[108:111], v[132:135], v[200:203], v[108:111]
	v_mfma_f32_16x16x32_bf16 v[108:111], v[148:151], v[220:223], v[108:111]
	v_mfma_f32_16x16x32_bf16 v[96:99], v[118:121], v[224:227], v[96:99]
	v_mfma_f32_16x16x32_bf16 v[96:99], v[122:125], v[228:231], v[96:99]
	v_mfma_f32_16x16x32_bf16 v[92:95], v[132:135], v[224:227], v[92:95]
	v_mfma_f32_16x16x32_bf16 v[92:95], v[148:151], v[228:231], v[92:95]
	v_mfma_f32_16x16x32_bf16 v[80:83], v[118:121], v[232:235], v[80:83]
	v_mfma_f32_16x16x32_bf16 v[80:83], v[122:125], v[236:239], v[80:83]
	v_mfma_f32_16x16x32_bf16 v[76:79], v[132:135], v[232:235], v[76:79]
	v_mfma_f32_16x16x32_bf16 v[76:79], v[148:151], v[236:239], v[76:79]
	v_mfma_f32_16x16x32_bf16 v[136:139], v[152:155], v[192:195], v[136:139]
	v_mfma_f32_16x16x32_bf16 v[136:139], v[156:159], v[196:199], v[136:139]
	v_mfma_f32_16x16x32_bf16 v[126:129], v[160:163], v[192:195], v[126:129]
	v_mfma_f32_16x16x32_bf16 v[104:107], v[152:155], v[200:203], v[104:107]
	v_mfma_f32_16x16x32_bf16 v[104:107], v[156:159], v[220:223], v[104:107]
	v_mfma_f32_16x16x32_bf16 v[100:103], v[160:163], v[200:203], v[100:103]
	v_mfma_f32_16x16x32_bf16 v[100:103], v[188:191], v[220:223], v[100:103]
	v_mfma_f32_16x16x32_bf16 v[88:91], v[152:155], v[224:227], v[88:91]
	v_mfma_f32_16x16x32_bf16 v[88:91], v[156:159], v[228:231], v[88:91]
	v_mfma_f32_16x16x32_bf16 v[84:87], v[160:163], v[224:227], v[84:87]
	v_mfma_f32_16x16x32_bf16 v[84:87], v[188:191], v[228:231], v[84:87]
	v_mfma_f32_16x16x32_bf16 v[72:75], v[152:155], v[232:235], v[72:75]
	v_mfma_f32_16x16x32_bf16 v[72:75], v[156:159], v[236:239], v[72:75]
	v_mfma_f32_16x16x32_bf16 v[68:71], v[160:163], v[232:235], v[68:71]
	v_mfma_f32_16x16x32_bf16 v[68:71], v[188:191], v[236:239], v[68:71]
	v_mfma_f32_16x16x32_bf16 v[128:131], v[188:191], v[196:199], v[126:129]
	s_barrier
	s_add_i32 s20, s20, s14
	v_lshl_add_u64 v[6:7], v[240:241], 0, s[34:35]
	s_mov_b32 m0, s20
	ds_read_b128 v[192:195], v218 offset:49152
	ds_read_b128 v[196:199], v218 offset:50176
	ds_read_b128 v[200:203], v218 offset:51200
	ds_read_b128 v[220:223], v218 offset:52224
	ds_read_b128 v[224:227], v218 offset:53248
	ds_read_b128 v[228:231], v218 offset:54272
	ds_read_b128 v[232:235], v218 offset:55296
	ds_read_b128 v[236:239], v218 offset:56320
	global_load_lds_dwordx4 v[6:7], off
	v_lshl_add_u64 v[6:7], v[240:241], 0, s[38:39]
	s_add_i32 m0, s20, 0x2000
	s_add_i32 s20, s21, s14
	global_load_lds_dwordx4 v[6:7], off
	v_lshl_add_u64 v[6:7], v[240:241], 0, s[44:45]
	s_mov_b32 m0, s20
	s_nop 0
	global_load_lds_dwordx4 v[6:7], off
	v_lshl_add_u64 v[6:7], v[240:241], 0, s[10:11]
	s_add_i32 m0, s20, 0x2000
	s_nop 0
	global_load_lds_dwordx4 v[6:7], off
	v_lshl_add_u64 v[6:7], v[242:243], 0, s[34:35]
	s_mov_b32 m0, s90
	s_nop 0
	global_load_lds_dwordx4 v[6:7], off
	v_lshl_add_u64 v[6:7], v[242:243], 0, s[38:39]
	s_mov_b32 m0, s91
	s_nop 0
	global_load_lds_dwordx4 v[6:7], off
	s_waitcnt vmcnt(8) lgkmcnt(0)
	s_barrier
	v_mfma_f32_16x16x32_bf16 v[64:67], v[118:121], v[192:195], v[64:67]
	v_mfma_f32_16x16x32_bf16 v[64:67], v[122:125], v[196:199], v[64:67]
	v_mfma_f32_16x16x32_bf16 v[60:63], v[132:135], v[192:195], v[60:63]
	v_mfma_f32_16x16x32_bf16 v[60:63], v[148:151], v[196:199], v[60:63]
	v_mfma_f32_16x16x32_bf16 v[48:51], v[118:121], v[200:203], v[48:51]
	v_mfma_f32_16x16x32_bf16 v[48:51], v[122:125], v[220:223], v[48:51]
	v_mfma_f32_16x16x32_bf16 v[44:47], v[132:135], v[200:203], v[44:47]
	v_mfma_f32_16x16x32_bf16 v[44:47], v[148:151], v[220:223], v[44:47]
	v_mfma_f32_16x16x32_bf16 v[32:35], v[118:121], v[224:227], v[32:35]
	v_mfma_f32_16x16x32_bf16 v[32:35], v[122:125], v[228:231], v[32:35]
	v_mfma_f32_16x16x32_bf16 v[28:31], v[132:135], v[224:227], v[28:31]
	v_mfma_f32_16x16x32_bf16 v[28:31], v[148:151], v[228:231], v[28:31]
	v_mfma_f32_16x16x32_bf16 v[16:19], v[118:121], v[232:235], v[16:19]
	v_mfma_f32_16x16x32_bf16 v[16:19], v[122:125], v[236:239], v[16:19]
	v_mfma_f32_16x16x32_bf16 v[12:15], v[132:135], v[232:235], v[12:15]
	v_mfma_f32_16x16x32_bf16 v[12:15], v[148:151], v[236:239], v[12:15]
	v_mfma_f32_16x16x32_bf16 v[56:59], v[152:155], v[192:195], v[56:59]
	v_mfma_f32_16x16x32_bf16 v[56:59], v[156:159], v[196:199], v[56:59]
	v_mfma_f32_16x16x32_bf16 v[52:55], v[160:163], v[192:195], v[52:55]
	v_mfma_f32_16x16x32_bf16 v[52:55], v[188:191], v[196:199], v[52:55]
	v_mfma_f32_16x16x32_bf16 v[40:43], v[152:155], v[200:203], v[40:43]
	v_mfma_f32_16x16x32_bf16 v[40:43], v[156:159], v[220:223], v[40:43]
	v_mfma_f32_16x16x32_bf16 v[36:39], v[160:163], v[200:203], v[36:39]
	v_mfma_f32_16x16x32_bf16 v[36:39], v[188:191], v[220:223], v[36:39]
	v_mfma_f32_16x16x32_bf16 v[24:27], v[152:155], v[224:227], v[24:27]
	v_mfma_f32_16x16x32_bf16 v[24:27], v[156:159], v[228:231], v[24:27]
	v_mfma_f32_16x16x32_bf16 v[20:23], v[160:163], v[224:227], v[20:23]
	v_mfma_f32_16x16x32_bf16 v[20:23], v[188:191], v[228:231], v[20:23]
	v_mfma_f32_16x16x32_bf16 v[6:9], v[152:155], v[232:235], v[8:11]
	v_mfma_f32_16x16x32_bf16 v[2:5], v[160:163], v[232:235], v[2:5]
	v_mfma_f32_16x16x32_bf16 v[8:11], v[156:159], v[236:239], v[6:9]
	v_mfma_f32_16x16x32_bf16 v[4:7], v[188:191], v[236:239], v[2:5]
	s_barrier
	s_add_i32 vcc_hi, vcc_hi, 2
	s_add_u32 s68, s68, 0x100
	s_addc_u32 s69, s69, 0
	s_cmp_gt_u32 vcc_hi, 13
	s_cbranch_scc1 .LBB0_565

.LBB0_604:
	s_add_i32 s22, 0, 0x10000
	s_add_i32 s23, 0, 0x14000
	v_add_u32_e32 v150, s22, v139
	v_add_u32_e32 v162, s23, v139
	ds_read_b128 v[134:137], v150
	ds_read_b128 v[142:145], v150 offset:1024
	ds_read_b128 v[146:149], v150 offset:2048
	ds_read_b128 v[150:153], v150 offset:3072
	ds_read_b128 v[154:157], v162
	ds_read_b128 v[158:161], v162 offset:1024
	ds_read_b128 v[182:185], v162 offset:2048
	ds_read_b128 v[186:189], v162 offset:3072
	ds_read_b128 v[190:193], v141
	ds_read_b128 v[194:197], v141 offset:1024
	ds_read_b128 v[198:201], v141 offset:2048
	ds_read_b128 v[214:217], v141 offset:3072
	ds_read_b128 v[218:221], v141 offset:4096
	ds_read_b128 v[222:225], v141 offset:5120
	ds_read_b128 v[226:229], v141 offset:6144
	ds_read_b128 v[230:233], v141 offset:7168
	s_add_u32 s20, s6, 0xfffe0080
	s_addc_u32 s21, s7, -1
	s_cmp_eq_u32 s84, 4
	s_cselect_b32 s69, s42, s21
	s_cselect_b32 s68, s43, s20
	s_cselect_b32 s21, s46, s51
	s_cselect_b32 s20, s47, s49
	s_add_i32 m0, s89, 0xc000
	v_lshl_add_u64 v[162:163], s[6:7], 0, v[132:133]
	global_load_lds_dwordx4 v[162:163], off
	v_lshl_add_u64 v[162:163], v[162:163], 0, s[64:65]
	s_add_i32 m0, s89, 0xe000
	s_nop 0
	global_load_lds_dwordx4 v[162:163], off
	s_waitcnt vmcnt(8) lgkmcnt(0)
	s_barrier
	v_mfma_f32_16x16x32_bf16 v[126:129], v[134:137], v[190:193], v[126:129]
	v_mfma_f32_16x16x32_bf16 v[126:129], v[142:145], v[194:197], v[126:129]
	v_mfma_f32_16x16x32_bf16 v[122:125], v[146:149], v[190:193], v[122:125]
	v_mfma_f32_16x16x32_bf16 v[122:125], v[150:153], v[194:197], v[122:125]
	v_mfma_f32_16x16x32_bf16 v[110:113], v[134:137], v[198:201], v[110:113]
	v_mfma_f32_16x16x32_bf16 v[110:113], v[142:145], v[214:217], v[110:113]
	v_mfma_f32_16x16x32_bf16 v[106:109], v[146:149], v[198:201], v[106:109]
	v_mfma_f32_16x16x32_bf16 v[106:109], v[150:153], v[214:217], v[106:109]
	v_mfma_f32_16x16x32_bf16 v[94:97], v[134:137], v[218:221], v[94:97]
	v_mfma_f32_16x16x32_bf16 v[94:97], v[142:145], v[222:225], v[94:97]
	v_mfma_f32_16x16x32_bf16 v[90:93], v[146:149], v[218:221], v[90:93]
	v_mfma_f32_16x16x32_bf16 v[90:93], v[150:153], v[222:225], v[90:93]
	v_mfma_f32_16x16x32_bf16 v[78:81], v[134:137], v[226:229], v[78:81]
	v_mfma_f32_16x16x32_bf16 v[78:81], v[142:145], v[230:233], v[78:81]
	v_mfma_f32_16x16x32_bf16 v[74:77], v[146:149], v[226:229], v[74:77]
	v_mfma_f32_16x16x32_bf16 v[74:77], v[150:153], v[230:233], v[74:77]
	v_mfma_f32_16x16x32_bf16 v[118:121], v[154:157], v[190:193], v[118:121]
	v_mfma_f32_16x16x32_bf16 v[118:121], v[158:161], v[194:197], v[118:121]
	v_mfma_f32_16x16x32_bf16 v[114:117], v[182:185], v[190:193], v[114:117]
	v_mfma_f32_16x16x32_bf16 v[114:117], v[186:189], v[194:197], v[114:117]
	v_mfma_f32_16x16x32_bf16 v[102:105], v[154:157], v[198:201], v[102:105]
	v_mfma_f32_16x16x32_bf16 v[102:105], v[158:161], v[214:217], v[102:105]
	v_mfma_f32_16x16x32_bf16 v[98:101], v[182:185], v[198:201], v[98:101]
	v_mfma_f32_16x16x32_bf16 v[98:101], v[186:189], v[214:217], v[98:101]
	v_mfma_f32_16x16x32_bf16 v[86:89], v[154:157], v[218:221], v[86:89]
	v_mfma_f32_16x16x32_bf16 v[86:89], v[158:161], v[222:225], v[86:89]
	v_mfma_f32_16x16x32_bf16 v[82:85], v[182:185], v[218:221], v[82:85]
	v_mfma_f32_16x16x32_bf16 v[82:85], v[186:189], v[222:225], v[82:85]
	v_mfma_f32_16x16x32_bf16 v[70:73], v[154:157], v[226:229], v[70:73]
	v_mfma_f32_16x16x32_bf16 v[70:73], v[158:161], v[230:233], v[70:73]
	v_mfma_f32_16x16x32_bf16 v[66:69], v[182:185], v[226:229], v[66:69]
	v_mfma_f32_16x16x32_bf16 v[66:69], v[186:189], v[230:233], v[66:69]
	s_barrier
	ds_read_b128 v[190:193], v141 offset:16384
	ds_read_b128 v[194:197], v141 offset:17408
	ds_read_b128 v[198:201], v141 offset:18432
	ds_read_b128 v[214:217], v141 offset:19456
	ds_read_b128 v[218:221], v141 offset:20480
	ds_read_b128 v[222:225], v141 offset:21504
	ds_read_b128 v[226:229], v141 offset:22528
	ds_read_b128 v[230:233], v141 offset:23552
	v_lshl_add_u64 v[162:163], s[20:21], 0, v[0:1]
	s_add_i32 s20, s22, s88
	s_mov_b32 m0, s20
	s_nop 0
	s_nop 0
	global_load_lds_dwordx4 v[162:163], off
	v_lshl_add_u64 v[202:203], v[162:163], 0, s[64:65]
	s_add_i32 m0, s20, 0x2000
	s_add_i32 s20, s23, s88
	global_load_lds_dwordx4 v[202:203], off
	v_lshl_add_u64 v[202:203], v[162:163], 0, s[72:73]
	s_mov_b32 m0, s20
	s_nop 0
	global_load_lds_dwordx4 v[202:203], off
	v_lshl_add_u64 v[202:203], v[162:163], 0, s[74:75]
	s_add_i32 m0, s20, 0x2000
	s_nop 0
	global_load_lds_dwordx4 v[202:203], off
	v_lshl_add_u64 v[202:203], s[68:69], 0, v[130:131]
	s_mov_b32 m0, s89
	v_lshl_add_u64 v[234:235], v[202:203], 0, s[64:65]
	global_load_lds_dwordx4 v[202:203], off
	s_mov_b32 m0, s90
	s_nop 0
	global_load_lds_dwordx4 v[234:235], off
	s_waitcnt vmcnt(8) lgkmcnt(0)
	s_barrier
	v_mfma_f32_16x16x32_bf16 v[62:65], v[134:137], v[190:193], v[62:65]
	v_mfma_f32_16x16x32_bf16 v[62:65], v[142:145], v[194:197], v[62:65]
	v_mfma_f32_16x16x32_bf16 v[58:61], v[146:149], v[190:193], v[58:61]
	v_mfma_f32_16x16x32_bf16 v[58:61], v[150:153], v[194:197], v[58:61]
	v_mfma_f32_16x16x32_bf16 v[46:49], v[134:137], v[198:201], v[46:49]
	v_mfma_f32_16x16x32_bf16 v[46:49], v[142:145], v[214:217], v[46:49]
	v_mfma_f32_16x16x32_bf16 v[42:45], v[146:149], v[198:201], v[42:45]
	v_mfma_f32_16x16x32_bf16 v[42:45], v[150:153], v[214:217], v[42:45]
	v_mfma_f32_16x16x32_bf16 v[30:33], v[134:137], v[218:221], v[30:33]
	v_mfma_f32_16x16x32_bf16 v[30:33], v[142:145], v[222:225], v[30:33]
	v_mfma_f32_16x16x32_bf16 v[26:29], v[146:149], v[218:221], v[26:29]
	v_mfma_f32_16x16x32_bf16 v[26:29], v[150:153], v[222:225], v[26:29]
	v_mfma_f32_16x16x32_bf16 v[14:17], v[134:137], v[226:229], v[14:17]
	v_mfma_f32_16x16x32_bf16 v[14:17], v[142:145], v[230:233], v[14:17]
	v_mfma_f32_16x16x32_bf16 v[10:13], v[146:149], v[226:229], v[10:13]
	v_mfma_f32_16x16x32_bf16 v[10:13], v[150:153], v[230:233], v[10:13]
	v_mfma_f32_16x16x32_bf16 v[54:57], v[154:157], v[190:193], v[54:57]
	v_mfma_f32_16x16x32_bf16 v[54:57], v[158:161], v[194:197], v[54:57]
	v_mfma_f32_16x16x32_bf16 v[50:53], v[182:185], v[190:193], v[50:53]
	v_mfma_f32_16x16x32_bf16 v[50:53], v[186:189], v[194:197], v[50:53]
	v_mfma_f32_16x16x32_bf16 v[38:41], v[154:157], v[198:201], v[38:41]
	v_mfma_f32_16x16x32_bf16 v[38:41], v[158:161], v[214:217], v[38:41]
	v_mfma_f32_16x16x32_bf16 v[34:37], v[182:185], v[198:201], v[34:37]
	v_mfma_f32_16x16x32_bf16 v[34:37], v[186:189], v[214:217], v[34:37]
	v_mfma_f32_16x16x32_bf16 v[22:25], v[154:157], v[218:221], v[22:25]
	v_mfma_f32_16x16x32_bf16 v[22:25], v[158:161], v[222:225], v[22:25]
	v_mfma_f32_16x16x32_bf16 v[18:21], v[182:185], v[218:221], v[18:21]
	v_mfma_f32_16x16x32_bf16 v[18:21], v[186:189], v[222:225], v[18:21]
	v_mfma_f32_16x16x32_bf16 v[6:9], v[154:157], v[226:229], v[6:9]
	v_mfma_f32_16x16x32_bf16 v[6:9], v[158:161], v[230:233], v[6:9]
	v_mfma_f32_16x16x32_bf16 v[2:5], v[182:185], v[226:229], v[2:5]
	v_mfma_f32_16x16x32_bf16 v[2:5], v[186:189], v[230:233], v[2:5]
	s_barrier
	s_add_i32 s20, 0, 0x18000
	s_add_i32 s21, 0, 0x1c000
	v_add_u32_e32 v150, s20, v139
	v_add_u32_e32 v186, s21, v139
	ds_read_b128 v[134:137], v150
	ds_read_b128 v[142:145], v150 offset:1024
	ds_read_b128 v[146:149], v150 offset:2048
	ds_read_b128 v[150:153], v150 offset:3072
	ds_read_b128 v[154:157], v186
	ds_read_b128 v[158:161], v186 offset:1024
	ds_read_b128 v[182:185], v186 offset:2048
	ds_read_b128 v[186:189], v186 offset:3072
	ds_read_b128 v[190:193], v141 offset:32768
	ds_read_b128 v[194:197], v141 offset:33792
	ds_read_b128 v[198:201], v141 offset:34816
	ds_read_b128 v[214:217], v141 offset:35840
	ds_read_b128 v[218:221], v141 offset:36864
	ds_read_b128 v[222:225], v141 offset:37888
	ds_read_b128 v[226:229], v141 offset:38912
	ds_read_b128 v[230:233], v141 offset:39936
	s_mov_b32 m0, s91
	v_lshl_add_u64 v[234:235], v[202:203], 0, s[72:73]
	global_load_lds_dwordx4 v[234:235], off
	v_lshl_add_u64 v[234:235], v[202:203], 0, s[74:75]
	s_mov_b32 m0, s96
	s_nop 0
	global_load_lds_dwordx4 v[234:235], off
	s_waitcnt vmcnt(8) lgkmcnt(0)
	s_barrier
	v_mfma_f32_16x16x32_bf16 v[126:129], v[134:137], v[190:193], v[126:129]
	v_mfma_f32_16x16x32_bf16 v[126:129], v[142:145], v[194:197], v[126:129]
	v_mfma_f32_16x16x32_bf16 v[122:125], v[146:149], v[190:193], v[122:125]
	v_mfma_f32_16x16x32_bf16 v[122:125], v[150:153], v[194:197], v[122:125]
	v_mfma_f32_16x16x32_bf16 v[110:113], v[134:137], v[198:201], v[110:113]
	v_mfma_f32_16x16x32_bf16 v[110:113], v[142:145], v[214:217], v[110:113]
	v_mfma_f32_16x16x32_bf16 v[106:109], v[146:149], v[198:201], v[106:109]
	v_mfma_f32_16x16x32_bf16 v[106:109], v[150:153], v[214:217], v[106:109]
	v_mfma_f32_16x16x32_bf16 v[94:97], v[134:137], v[218:221], v[94:97]
	v_mfma_f32_16x16x32_bf16 v[94:97], v[142:145], v[222:225], v[94:97]
	v_mfma_f32_16x16x32_bf16 v[90:93], v[146:149], v[218:221], v[90:93]
	v_mfma_f32_16x16x32_bf16 v[90:93], v[150:153], v[222:225], v[90:93]
	v_mfma_f32_16x16x32_bf16 v[78:81], v[134:137], v[226:229], v[78:81]
	v_mfma_f32_16x16x32_bf16 v[78:81], v[142:145], v[230:233], v[78:81]
	v_mfma_f32_16x16x32_bf16 v[74:77], v[146:149], v[226:229], v[74:77]
	v_mfma_f32_16x16x32_bf16 v[74:77], v[150:153], v[230:233], v[74:77]
	v_mfma_f32_16x16x32_bf16 v[118:121], v[154:157], v[190:193], v[118:121]
	v_mfma_f32_16x16x32_bf16 v[118:121], v[158:161], v[194:197], v[118:121]
	v_mfma_f32_16x16x32_bf16 v[114:117], v[182:185], v[190:193], v[114:117]
	v_mfma_f32_16x16x32_bf16 v[114:117], v[186:189], v[194:197], v[114:117]
	v_mfma_f32_16x16x32_bf16 v[102:105], v[154:157], v[198:201], v[102:105]
	v_mfma_f32_16x16x32_bf16 v[102:105], v[158:161], v[214:217], v[102:105]
	v_mfma_f32_16x16x32_bf16 v[98:101], v[182:185], v[198:201], v[98:101]
	v_mfma_f32_16x16x32_bf16 v[98:101], v[186:189], v[214:217], v[98:101]
	v_mfma_f32_16x16x32_bf16 v[86:89], v[154:157], v[218:221], v[86:89]
	v_mfma_f32_16x16x32_bf16 v[86:89], v[158:161], v[222:225], v[86:89]
	v_mfma_f32_16x16x32_bf16 v[82:85], v[182:185], v[218:221], v[82:85]
	v_mfma_f32_16x16x32_bf16 v[82:85], v[186:189], v[222:225], v[82:85]
	v_mfma_f32_16x16x32_bf16 v[70:73], v[154:157], v[226:229], v[70:73]
	v_mfma_f32_16x16x32_bf16 v[70:73], v[158:161], v[230:233], v[70:73]
	v_mfma_f32_16x16x32_bf16 v[66:69], v[182:185], v[226:229], v[66:69]
	v_mfma_f32_16x16x32_bf16 v[66:69], v[186:189], v[230:233], v[66:69]
	s_barrier
	ds_read_b128 v[190:193], v141 offset:49152
	ds_read_b128 v[194:197], v141 offset:50176
	ds_read_b128 v[198:201], v141 offset:51200
	ds_read_b128 v[214:217], v141 offset:52224
	ds_read_b128 v[218:221], v141 offset:53248
	ds_read_b128 v[222:225], v141 offset:54272
	ds_read_b128 v[226:229], v141 offset:55296
	ds_read_b128 v[230:233], v141 offset:56320
	s_add_i32 s20, s20, s88
	s_mov_b32 m0, s20
	v_lshl_add_u64 v[234:235], v[162:163], 0, s[34:35]
	global_load_lds_dwordx4 v[234:235], off
	v_lshl_add_u64 v[234:235], v[162:163], 0, s[80:81]
	s_add_i32 m0, s20, 0x2000
	s_add_i32 s20, s21, s88
	global_load_lds_dwordx4 v[234:235], off
	v_lshl_add_u64 v[234:235], v[162:163], 0, s[38:39]
	s_mov_b32 m0, s20
	v_lshl_add_u64 v[162:163], v[162:163], 0, s[86:87]
	global_load_lds_dwordx4 v[234:235], off
	s_add_i32 m0, s20, 0x2000
	s_nop 0
	global_load_lds_dwordx4 v[162:163], off
	v_lshl_add_u64 v[162:163], v[202:203], 0, s[34:35]
	s_mov_b32 m0, s97
	s_nop 0
	global_load_lds_dwordx4 v[162:163], off
	v_lshl_add_u64 v[162:163], v[202:203], 0, s[80:81]
	s_mov_b32 m0, s58
	s_nop 0
	global_load_lds_dwordx4 v[162:163], off
	s_waitcnt vmcnt(8) lgkmcnt(0)
	s_barrier
	v_mfma_f32_16x16x32_bf16 v[62:65], v[134:137], v[190:193], v[62:65]
	v_mfma_f32_16x16x32_bf16 v[62:65], v[142:145], v[194:197], v[62:65]
	v_mfma_f32_16x16x32_bf16 v[58:61], v[146:149], v[190:193], v[58:61]
	v_mfma_f32_16x16x32_bf16 v[58:61], v[150:153], v[194:197], v[58:61]
	v_mfma_f32_16x16x32_bf16 v[46:49], v[134:137], v[198:201], v[46:49]
	v_mfma_f32_16x16x32_bf16 v[46:49], v[142:145], v[214:217], v[46:49]
	v_mfma_f32_16x16x32_bf16 v[42:45], v[146:149], v[198:201], v[42:45]
	v_mfma_f32_16x16x32_bf16 v[42:45], v[150:153], v[214:217], v[42:45]
	v_mfma_f32_16x16x32_bf16 v[30:33], v[134:137], v[218:221], v[30:33]
	v_mfma_f32_16x16x32_bf16 v[30:33], v[142:145], v[222:225], v[30:33]
	v_mfma_f32_16x16x32_bf16 v[26:29], v[146:149], v[218:221], v[26:29]
	v_mfma_f32_16x16x32_bf16 v[26:29], v[150:153], v[222:225], v[26:29]
	v_mfma_f32_16x16x32_bf16 v[14:17], v[134:137], v[226:229], v[14:17]
	v_mfma_f32_16x16x32_bf16 v[14:17], v[142:145], v[230:233], v[14:17]
	v_mfma_f32_16x16x32_bf16 v[10:13], v[146:149], v[226:229], v[10:13]
	v_mfma_f32_16x16x32_bf16 v[10:13], v[150:153], v[230:233], v[10:13]
	s_add_i32 s84, s84, 2
	s_add_u32 s6, s6, 0x100
	s_addc_u32 s7, s7, 0
	s_add_u32 s49, s49, 0x100
	s_addc_u32 s51, s51, 0
	s_cmp_gt_u32 s84, 5
	v_mfma_f32_16x16x32_bf16 v[54:57], v[154:157], v[190:193], v[54:57]
	v_mfma_f32_16x16x32_bf16 v[54:57], v[158:161], v[194:197], v[54:57]
	v_mfma_f32_16x16x32_bf16 v[50:53], v[182:185], v[190:193], v[50:53]
	v_mfma_f32_16x16x32_bf16 v[50:53], v[186:189], v[194:197], v[50:53]
	v_mfma_f32_16x16x32_bf16 v[38:41], v[154:157], v[198:201], v[38:41]
	v_mfma_f32_16x16x32_bf16 v[38:41], v[158:161], v[214:217], v[38:41]
	v_mfma_f32_16x16x32_bf16 v[34:37], v[182:185], v[198:201], v[34:37]
	v_mfma_f32_16x16x32_bf16 v[34:37], v[186:189], v[214:217], v[34:37]
	v_mfma_f32_16x16x32_bf16 v[22:25], v[154:157], v[218:221], v[22:25]
	v_mfma_f32_16x16x32_bf16 v[22:25], v[158:161], v[222:225], v[22:25]
	v_mfma_f32_16x16x32_bf16 v[18:21], v[182:185], v[218:221], v[18:21]
	v_mfma_f32_16x16x32_bf16 v[18:21], v[186:189], v[222:225], v[18:21]
	v_mfma_f32_16x16x32_bf16 v[6:9], v[154:157], v[226:229], v[6:9]
	v_mfma_f32_16x16x32_bf16 v[6:9], v[158:161], v[230:233], v[6:9]
	v_mfma_f32_16x16x32_bf16 v[2:5], v[182:185], v[226:229], v[2:5]
	v_mfma_f32_16x16x32_bf16 v[2:5], v[186:189], v[230:233], v[2:5]
	s_barrier
	s_cbranch_scc0 .LBB0_604
	s_setprio 0
	s_and_b64 vcc, exec, s[52:53]
	s_cbranch_vccz .LBB0_607
	s_barrier

.LBB0_642:
	s_add_u32 s88, s60, s76
	s_addc_u32 s89, s61, s77
	s_add_u32 s22, s88, 0x100
	s_addc_u32 s23, s89, 0
	s_and_b64 s[20:21], s[68:69], exec
	s_cselect_b32 s78, s84, s22
	s_cselect_b32 s79, s51, s23
	s_add_u32 s20, s58, s76
	s_addc_u32 s21, s59, s77
	s_add_u32 s22, s20, 0x100
	s_addc_u32 s23, s21, 0
	s_add_i32 s40, 0, 0x10000
	s_and_b64 s[20:21], s[68:69], exec
	s_cselect_b32 s68, s85, s22
	s_cselect_b32 s69, s49, s23
	s_add_i32 s20, 0, 0x14000
	v_add_u32_e32 v148, s40, v133
	v_add_u32_e32 v182, s20, v133
	ds_read_b128 v[136:139], v148
	ds_read_b128 v[140:143], v148 offset:1024
	ds_read_b128 v[144:147], v148 offset:2048
	ds_read_b128 v[148:151], v148 offset:3072
	ds_read_b128 v[152:155], v182
	ds_read_b128 v[156:159], v182 offset:1024
	ds_read_b128 v[160:163], v182 offset:2048
	ds_read_b128 v[182:185], v182 offset:3072
	s_add_i32 s86, 0, 0x18000
	s_add_i32 s77, 0, 0x1c000
	s_add_i32 vcc_hi, s40, s46
	s_add_i32 vcc_lo, s20, s46
	s_add_i32 s76, s86, s46
	s_add_i32 s43, s77, s46
	s_add_i32 m0, s47, 0xc000
	s_add_i32 s21, s47, 0xe000
	s_add_i32 s42, vcc_hi, 0x2000
	s_add_i32 s87, vcc_lo, 0x2000
	s_add_i32 s41, s76, 0x2000
	s_add_i32 s40, s43, 0x2000
	v_lshl_add_u64 v[202:203], s[88:89], 0, v[130:131]
	v_lshl_add_u64 v[230:231], v[202:203], 0, s[80:81]
	ds_read_b128 v[186:189], v135
	ds_read_b128 v[190:193], v135 offset:1024
	ds_read_b128 v[194:197], v135 offset:2048
	ds_read_b128 v[198:201], v135 offset:3072
	ds_read_b128 v[214:217], v135 offset:4096
	ds_read_b128 v[218:221], v135 offset:5120
	ds_read_b128 v[222:225], v135 offset:6144
	ds_read_b128 v[226:229], v135 offset:7168
	global_load_lds_dwordx4 v[230:231], off
	v_lshl_add_u64 v[202:203], v[202:203], 0, s[30:31]
	s_mov_b32 m0, s21
	s_nop 0
	global_load_lds_dwordx4 v[202:203], off
	s_waitcnt vmcnt(8) lgkmcnt(0)
	s_barrier
	v_mfma_f32_16x16x32_bf16 v[126:129], v[136:139], v[186:189], v[126:129]
	v_mfma_f32_16x16x32_bf16 v[126:129], v[140:143], v[190:193], v[126:129]
	v_mfma_f32_16x16x32_bf16 v[122:125], v[144:147], v[186:189], v[122:125]
	v_mfma_f32_16x16x32_bf16 v[122:125], v[148:151], v[190:193], v[122:125]
	v_mfma_f32_16x16x32_bf16 v[118:121], v[136:139], v[194:197], v[118:121]
	v_mfma_f32_16x16x32_bf16 v[118:121], v[140:143], v[198:201], v[118:121]
	v_mfma_f32_16x16x32_bf16 v[110:113], v[144:147], v[194:197], v[110:113]
	v_mfma_f32_16x16x32_bf16 v[110:113], v[148:151], v[198:201], v[110:113]
	v_mfma_f32_16x16x32_bf16 v[102:105], v[136:139], v[214:217], v[102:105]
	v_mfma_f32_16x16x32_bf16 v[102:105], v[140:143], v[218:221], v[102:105]
	v_mfma_f32_16x16x32_bf16 v[94:97], v[144:147], v[214:217], v[94:97]
	v_mfma_f32_16x16x32_bf16 v[94:97], v[148:151], v[218:221], v[94:97]
	v_mfma_f32_16x16x32_bf16 v[86:89], v[136:139], v[222:225], v[86:89]
	v_mfma_f32_16x16x32_bf16 v[86:89], v[140:143], v[226:229], v[86:89]
	v_mfma_f32_16x16x32_bf16 v[78:81], v[144:147], v[222:225], v[78:81]
	v_mfma_f32_16x16x32_bf16 v[78:81], v[148:151], v[226:229], v[78:81]
	v_mfma_f32_16x16x32_bf16 v[114:117], v[152:155], v[186:189], v[114:117]
	v_mfma_f32_16x16x32_bf16 v[114:117], v[156:159], v[190:193], v[114:117]
	v_mfma_f32_16x16x32_bf16 v[106:109], v[160:163], v[186:189], v[106:109]
	v_mfma_f32_16x16x32_bf16 v[106:109], v[182:185], v[190:193], v[106:109]
	v_mfma_f32_16x16x32_bf16 v[98:101], v[152:155], v[194:197], v[98:101]
	v_mfma_f32_16x16x32_bf16 v[98:101], v[156:159], v[198:201], v[98:101]
	v_mfma_f32_16x16x32_bf16 v[90:93], v[160:163], v[194:197], v[90:93]
	v_mfma_f32_16x16x32_bf16 v[90:93], v[182:185], v[198:201], v[90:93]
	v_mfma_f32_16x16x32_bf16 v[82:85], v[152:155], v[214:217], v[82:85]
	v_mfma_f32_16x16x32_bf16 v[82:85], v[156:159], v[218:221], v[82:85]
	v_mfma_f32_16x16x32_bf16 v[74:77], v[160:163], v[214:217], v[74:77]
	v_mfma_f32_16x16x32_bf16 v[74:77], v[182:185], v[218:221], v[74:77]
	v_mfma_f32_16x16x32_bf16 v[70:73], v[152:155], v[222:225], v[70:73]
	v_mfma_f32_16x16x32_bf16 v[70:73], v[156:159], v[226:229], v[70:73]
	v_mfma_f32_16x16x32_bf16 v[66:69], v[160:163], v[222:225], v[66:69]
	v_mfma_f32_16x16x32_bf16 v[66:69], v[182:185], v[226:229], v[66:69]
	s_barrier
	s_mov_b32 m0, vcc_hi
	v_lshl_add_u64 v[202:203], s[68:69], 0, v[0:1]
	ds_read_b128 v[186:189], v135 offset:16384
	ds_read_b128 v[190:193], v135 offset:17408
	ds_read_b128 v[194:197], v135 offset:18432
	ds_read_b128 v[198:201], v135 offset:19456
	ds_read_b128 v[214:217], v135 offset:20480
	ds_read_b128 v[218:221], v135 offset:21504
	ds_read_b128 v[222:225], v135 offset:22528
	ds_read_b128 v[226:229], v135 offset:23552
	global_load_lds_dwordx4 v[202:203], off
	v_lshl_add_u64 v[230:231], v[202:203], 0, s[36:37]
	s_mov_b32 m0, s42
	s_nop 0
	global_load_lds_dwordx4 v[230:231], off
	v_lshl_add_u64 v[230:231], v[202:203], 0, s[64:65]
	s_mov_b32 m0, vcc_lo
	s_nop 0
	global_load_lds_dwordx4 v[230:231], off
	v_lshl_add_u64 v[230:231], v[202:203], 0, s[8:9]
	s_mov_b32 m0, s87
	s_nop 0
	global_load_lds_dwordx4 v[230:231], off
	v_lshl_add_u64 v[230:231], s[78:79], 0, v[130:131]
	s_mov_b32 m0, s47
	v_lshl_add_u64 v[232:233], v[230:231], 0, s[36:37]
	global_load_lds_dwordx4 v[230:231], off
	s_mov_b32 m0, s90
	s_nop 0
	global_load_lds_dwordx4 v[232:233], off
	s_waitcnt vmcnt(8) lgkmcnt(0)
	s_barrier
	v_mfma_f32_16x16x32_bf16 v[62:65], v[136:139], v[186:189], v[62:65]
	v_mfma_f32_16x16x32_bf16 v[62:65], v[140:143], v[190:193], v[62:65]
	v_mfma_f32_16x16x32_bf16 v[58:61], v[144:147], v[186:189], v[58:61]
	v_mfma_f32_16x16x32_bf16 v[58:61], v[148:151], v[190:193], v[58:61]
	v_mfma_f32_16x16x32_bf16 v[54:57], v[136:139], v[194:197], v[54:57]
	v_mfma_f32_16x16x32_bf16 v[54:57], v[140:143], v[198:201], v[54:57]
	v_mfma_f32_16x16x32_bf16 v[46:49], v[144:147], v[194:197], v[46:49]
	v_mfma_f32_16x16x32_bf16 v[46:49], v[148:151], v[198:201], v[46:49]
	v_mfma_f32_16x16x32_bf16 v[38:41], v[136:139], v[214:217], v[38:41]
	v_mfma_f32_16x16x32_bf16 v[38:41], v[140:143], v[218:221], v[38:41]
	v_mfma_f32_16x16x32_bf16 v[30:33], v[144:147], v[214:217], v[30:33]
	v_mfma_f32_16x16x32_bf16 v[30:33], v[148:151], v[218:221], v[30:33]
	v_mfma_f32_16x16x32_bf16 v[22:25], v[136:139], v[222:225], v[22:25]
	v_mfma_f32_16x16x32_bf16 v[22:25], v[140:143], v[226:229], v[22:25]
	v_mfma_f32_16x16x32_bf16 v[14:17], v[144:147], v[222:225], v[14:17]
	v_mfma_f32_16x16x32_bf16 v[14:17], v[148:151], v[226:229], v[14:17]
	v_mfma_f32_16x16x32_bf16 v[50:53], v[152:155], v[186:189], v[50:53]
	v_mfma_f32_16x16x32_bf16 v[50:53], v[156:159], v[190:193], v[50:53]
	v_mfma_f32_16x16x32_bf16 v[42:45], v[160:163], v[186:189], v[42:45]
	v_mfma_f32_16x16x32_bf16 v[42:45], v[182:185], v[190:193], v[42:45]
	v_mfma_f32_16x16x32_bf16 v[34:37], v[152:155], v[194:197], v[34:37]
	v_mfma_f32_16x16x32_bf16 v[34:37], v[156:159], v[198:201], v[34:37]
	v_mfma_f32_16x16x32_bf16 v[26:29], v[160:163], v[194:197], v[26:29]
	v_mfma_f32_16x16x32_bf16 v[26:29], v[182:185], v[198:201], v[26:29]
	v_mfma_f32_16x16x32_bf16 v[18:21], v[152:155], v[214:217], v[18:21]
	v_mfma_f32_16x16x32_bf16 v[18:21], v[156:159], v[218:221], v[18:21]
	v_mfma_f32_16x16x32_bf16 v[10:13], v[160:163], v[214:217], v[10:13]
	v_mfma_f32_16x16x32_bf16 v[10:13], v[182:185], v[218:221], v[10:13]
	v_mfma_f32_16x16x32_bf16 v[6:9], v[152:155], v[222:225], v[6:9]
	v_mfma_f32_16x16x32_bf16 v[6:9], v[156:159], v[226:229], v[6:9]
	v_mfma_f32_16x16x32_bf16 v[2:5], v[160:163], v[222:225], v[2:5]
	v_mfma_f32_16x16x32_bf16 v[2:5], v[182:185], v[226:229], v[2:5]
	s_barrier
	v_add_u32_e32 v148, s86, v133
	v_add_u32_e32 v182, s77, v133
	ds_read_b128 v[136:139], v148
	ds_read_b128 v[140:143], v148 offset:1024
	ds_read_b128 v[144:147], v148 offset:2048
	ds_read_b128 v[148:151], v148 offset:3072
	ds_read_b128 v[152:155], v182
	ds_read_b128 v[156:159], v182 offset:1024
	ds_read_b128 v[160:163], v182 offset:2048
	ds_read_b128 v[182:185], v182 offset:3072
	s_mov_b32 m0, s91
	v_lshl_add_u64 v[232:233], v[230:231], 0, s[64:65]
	ds_read_b128 v[186:189], v135 offset:32768
	ds_read_b128 v[190:193], v135 offset:33792
	ds_read_b128 v[194:197], v135 offset:34816
	ds_read_b128 v[198:201], v135 offset:35840
	ds_read_b128 v[214:217], v135 offset:36864
	ds_read_b128 v[218:221], v135 offset:37888
	ds_read_b128 v[222:225], v135 offset:38912
	ds_read_b128 v[226:229], v135 offset:39936
	global_load_lds_dwordx4 v[232:233], off
	v_lshl_add_u64 v[232:233], v[230:231], 0, s[8:9]
	s_mov_b32 m0, s96
	s_nop 0
	global_load_lds_dwordx4 v[232:233], off
	s_waitcnt vmcnt(8) lgkmcnt(0)
	s_barrier
	v_mfma_f32_16x16x32_bf16 v[126:129], v[136:139], v[186:189], v[126:129]
	v_mfma_f32_16x16x32_bf16 v[126:129], v[140:143], v[190:193], v[126:129]
	v_mfma_f32_16x16x32_bf16 v[122:125], v[144:147], v[186:189], v[122:125]
	v_mfma_f32_16x16x32_bf16 v[122:125], v[148:151], v[190:193], v[122:125]
	v_mfma_f32_16x16x32_bf16 v[118:121], v[136:139], v[194:197], v[118:121]
	v_mfma_f32_16x16x32_bf16 v[118:121], v[140:143], v[198:201], v[118:121]
	v_mfma_f32_16x16x32_bf16 v[110:113], v[144:147], v[194:197], v[110:113]
	v_mfma_f32_16x16x32_bf16 v[110:113], v[148:151], v[198:201], v[110:113]
	v_mfma_f32_16x16x32_bf16 v[102:105], v[136:139], v[214:217], v[102:105]
	v_mfma_f32_16x16x32_bf16 v[102:105], v[140:143], v[218:221], v[102:105]
	v_mfma_f32_16x16x32_bf16 v[94:97], v[144:147], v[214:217], v[94:97]
	v_mfma_f32_16x16x32_bf16 v[94:97], v[148:151], v[218:221], v[94:97]
	v_mfma_f32_16x16x32_bf16 v[86:89], v[136:139], v[222:225], v[86:89]
	v_mfma_f32_16x16x32_bf16 v[86:89], v[140:143], v[226:229], v[86:89]
	v_mfma_f32_16x16x32_bf16 v[78:81], v[144:147], v[222:225], v[78:81]
	v_mfma_f32_16x16x32_bf16 v[78:81], v[148:151], v[226:229], v[78:81]
	v_mfma_f32_16x16x32_bf16 v[114:117], v[152:155], v[186:189], v[114:117]
	v_mfma_f32_16x16x32_bf16 v[114:117], v[156:159], v[190:193], v[114:117]
	v_mfma_f32_16x16x32_bf16 v[106:109], v[160:163], v[186:189], v[106:109]
	v_mfma_f32_16x16x32_bf16 v[106:109], v[182:185], v[190:193], v[106:109]
	v_mfma_f32_16x16x32_bf16 v[98:101], v[152:155], v[194:197], v[98:101]
	v_mfma_f32_16x16x32_bf16 v[98:101], v[156:159], v[198:201], v[98:101]
	v_mfma_f32_16x16x32_bf16 v[90:93], v[160:163], v[194:197], v[90:93]
	v_mfma_f32_16x16x32_bf16 v[90:93], v[182:185], v[198:201], v[90:93]
	v_mfma_f32_16x16x32_bf16 v[82:85], v[152:155], v[214:217], v[82:85]
	v_mfma_f32_16x16x32_bf16 v[82:85], v[156:159], v[218:221], v[82:85]
	v_mfma_f32_16x16x32_bf16 v[74:77], v[160:163], v[214:217], v[74:77]
	v_mfma_f32_16x16x32_bf16 v[74:77], v[182:185], v[218:221], v[74:77]
	v_mfma_f32_16x16x32_bf16 v[70:73], v[152:155], v[222:225], v[70:73]
	v_mfma_f32_16x16x32_bf16 v[70:73], v[156:159], v[226:229], v[70:73]
	v_mfma_f32_16x16x32_bf16 v[66:69], v[160:163], v[222:225], v[66:69]
	v_mfma_f32_16x16x32_bf16 v[66:69], v[182:185], v[226:229], v[66:69]
	s_barrier
	s_mov_b32 m0, s76
	v_lshl_add_u64 v[232:233], v[202:203], 0, s[34:35]
	ds_read_b128 v[186:189], v135 offset:49152
	ds_read_b128 v[190:193], v135 offset:50176
	ds_read_b128 v[194:197], v135 offset:51200
	ds_read_b128 v[198:201], v135 offset:52224
	ds_read_b128 v[214:217], v135 offset:53248
	ds_read_b128 v[218:221], v135 offset:54272
	ds_read_b128 v[222:225], v135 offset:55296
	ds_read_b128 v[226:229], v135 offset:56320
	global_load_lds_dwordx4 v[232:233], off
	v_lshl_add_u64 v[232:233], v[202:203], 0, s[70:71]
	s_mov_b32 m0, s41
	s_nop 0
	global_load_lds_dwordx4 v[232:233], off
	v_lshl_add_u64 v[232:233], v[202:203], 0, s[80:81]
	s_mov_b32 m0, s43
	v_lshl_add_u64 v[202:203], v[202:203], 0, s[30:31]
	global_load_lds_dwordx4 v[232:233], off
	s_mov_b32 m0, s40
	s_nop 0
	global_load_lds_dwordx4 v[202:203], off
	v_lshl_add_u64 v[202:203], v[230:231], 0, s[34:35]
	s_mov_b32 m0, s97
	s_nop 0
	global_load_lds_dwordx4 v[202:203], off
	v_lshl_add_u64 v[202:203], v[230:231], 0, s[70:71]
	s_mov_b32 m0, s0
	s_nop 0
	global_load_lds_dwordx4 v[202:203], off
	s_waitcnt vmcnt(8) lgkmcnt(0)
	s_barrier
	v_mfma_f32_16x16x32_bf16 v[62:65], v[136:139], v[186:189], v[62:65]
	v_mfma_f32_16x16x32_bf16 v[62:65], v[140:143], v[190:193], v[62:65]
	v_mfma_f32_16x16x32_bf16 v[58:61], v[144:147], v[186:189], v[58:61]
	v_mfma_f32_16x16x32_bf16 v[58:61], v[148:151], v[190:193], v[58:61]
	v_mfma_f32_16x16x32_bf16 v[54:57], v[136:139], v[194:197], v[54:57]
	v_mfma_f32_16x16x32_bf16 v[54:57], v[140:143], v[198:201], v[54:57]
	v_mfma_f32_16x16x32_bf16 v[46:49], v[144:147], v[194:197], v[46:49]
	v_mfma_f32_16x16x32_bf16 v[46:49], v[148:151], v[198:201], v[46:49]
	v_mfma_f32_16x16x32_bf16 v[38:41], v[136:139], v[214:217], v[38:41]
	v_mfma_f32_16x16x32_bf16 v[38:41], v[140:143], v[218:221], v[38:41]
	v_mfma_f32_16x16x32_bf16 v[30:33], v[144:147], v[214:217], v[30:33]
	v_mfma_f32_16x16x32_bf16 v[30:33], v[148:151], v[218:221], v[30:33]
	v_mfma_f32_16x16x32_bf16 v[22:25], v[136:139], v[222:225], v[22:25]
	v_mfma_f32_16x16x32_bf16 v[22:25], v[140:143], v[226:229], v[22:25]
	v_mfma_f32_16x16x32_bf16 v[14:17], v[144:147], v[222:225], v[14:17]
	v_mfma_f32_16x16x32_bf16 v[14:17], v[148:151], v[226:229], v[14:17]
	v_mfma_f32_16x16x32_bf16 v[50:53], v[152:155], v[186:189], v[50:53]
	v_mfma_f32_16x16x32_bf16 v[50:53], v[156:159], v[190:193], v[50:53]
	v_mfma_f32_16x16x32_bf16 v[42:45], v[160:163], v[186:189], v[42:45]
	v_mfma_f32_16x16x32_bf16 v[42:45], v[182:185], v[190:193], v[42:45]
	v_mfma_f32_16x16x32_bf16 v[34:37], v[152:155], v[194:197], v[34:37]
	v_mfma_f32_16x16x32_bf16 v[34:37], v[156:159], v[198:201], v[34:37]
	v_mfma_f32_16x16x32_bf16 v[26:29], v[160:163], v[194:197], v[26:29]
	v_mfma_f32_16x16x32_bf16 v[26:29], v[182:185], v[198:201], v[26:29]
	v_mfma_f32_16x16x32_bf16 v[18:21], v[152:155], v[214:217], v[18:21]
	v_mfma_f32_16x16x32_bf16 v[18:21], v[156:159], v[218:221], v[18:21]
	v_mfma_f32_16x16x32_bf16 v[10:13], v[160:163], v[214:217], v[10:13]
	v_mfma_f32_16x16x32_bf16 v[10:13], v[182:185], v[218:221], v[10:13]
	v_mfma_f32_16x16x32_bf16 v[6:9], v[152:155], v[222:225], v[6:9]
	v_mfma_f32_16x16x32_bf16 v[6:9], v[156:159], v[226:229], v[6:9]
	v_mfma_f32_16x16x32_bf16 v[2:5], v[160:163], v[222:225], v[2:5]
	v_mfma_f32_16x16x32_bf16 v[2:5], v[182:185], v[226:229], v[2:5]
	s_barrier
	s_andn2_b64 vcc, exec, s[62:63]
	s_mov_b64 s[68:69], -1
	s_mov_b64 s[62:63], 0
	s_mov_b64 s[76:77], 0x100
	s_cbranch_vccz .LBB0_642
	v_readlane_b32 s12, v244, 8
	v_readlane_b32 s13, v244, 9
	s_and_b64 vcc, exec, s[12:13]
	v_readlane_b32 s85, v244, 4
	s_cbranch_vccz .LBB0_645
	s_barrier

.LBB0_778:
	s_add_i32 s22, 0, 0x10000
	s_add_i32 s23, 0, 0x14000
	v_add_u32_e32 v142, s22, v193
	v_add_u32_e32 v158, s23, v193
	ds_read_b128 v[130:133], v142
	ds_read_b128 v[134:137], v142 offset:1024
	ds_read_b128 v[138:141], v142 offset:2048
	ds_read_b128 v[142:145], v142 offset:3072
	ds_read_b128 v[146:149], v158
	ds_read_b128 v[150:153], v158 offset:1024
	ds_read_b128 v[154:157], v158 offset:2048
	ds_read_b128 v[158:161], v158 offset:3072
	ds_read_b128 v[184:187], v196
	ds_read_b128 v[188:191], v196 offset:1024
	ds_read_b128 v[198:201], v196 offset:2048
	ds_read_b128 v[214:217], v196 offset:3072
	ds_read_b128 v[218:221], v196 offset:4096
	ds_read_b128 v[222:225], v196 offset:5120
	ds_read_b128 v[226:229], v196 offset:6144
	ds_read_b128 v[230:233], v196 offset:7168
	s_add_u32 s20, s76, 0xfffc0080
	s_addc_u32 s21, s77, -1
	s_cmp_eq_u32 vcc_hi, 12
	s_cselect_b32 s79, s61, s21
	s_cselect_b32 s78, s85, s20
	s_cselect_b32 s21, s59, vcc_lo
	s_cselect_b32 s20, s86, s87
	s_add_i32 m0, s43, 0xc000
	v_lshl_add_u64 v[202:203], s[76:77], 0, v[182:183]
	global_load_lds_dwordx4 v[202:203], off
	v_lshl_add_u64 v[202:203], v[202:203], 0, s[72:73]
	s_add_i32 m0, s43, 0xe000
	s_nop 0
	global_load_lds_dwordx4 v[202:203], off
	s_waitcnt vmcnt(8) lgkmcnt(0)
	s_barrier
	v_mfma_f32_16x16x32_bf16 v[126:129], v[130:133], v[184:187], v[126:129]
	v_mfma_f32_16x16x32_bf16 v[126:129], v[134:137], v[188:191], v[126:129]
	v_mfma_f32_16x16x32_bf16 v[122:125], v[138:141], v[184:187], v[122:125]
	v_mfma_f32_16x16x32_bf16 v[122:125], v[142:145], v[188:191], v[122:125]
	v_mfma_f32_16x16x32_bf16 v[110:113], v[130:133], v[198:201], v[110:113]
	v_mfma_f32_16x16x32_bf16 v[110:113], v[134:137], v[214:217], v[110:113]
	v_mfma_f32_16x16x32_bf16 v[106:109], v[138:141], v[198:201], v[106:109]
	v_mfma_f32_16x16x32_bf16 v[106:109], v[142:145], v[214:217], v[106:109]
	v_mfma_f32_16x16x32_bf16 v[94:97], v[130:133], v[218:221], v[94:97]
	v_mfma_f32_16x16x32_bf16 v[94:97], v[134:137], v[222:225], v[94:97]
	v_mfma_f32_16x16x32_bf16 v[90:93], v[138:141], v[218:221], v[90:93]
	v_mfma_f32_16x16x32_bf16 v[90:93], v[142:145], v[222:225], v[90:93]
	v_mfma_f32_16x16x32_bf16 v[78:81], v[130:133], v[226:229], v[78:81]
	v_mfma_f32_16x16x32_bf16 v[78:81], v[134:137], v[230:233], v[78:81]
	v_mfma_f32_16x16x32_bf16 v[74:77], v[138:141], v[226:229], v[74:77]
	v_mfma_f32_16x16x32_bf16 v[74:77], v[142:145], v[230:233], v[74:77]
	v_mfma_f32_16x16x32_bf16 v[118:121], v[146:149], v[184:187], v[118:121]
	v_mfma_f32_16x16x32_bf16 v[118:121], v[150:153], v[188:191], v[118:121]
	v_mfma_f32_16x16x32_bf16 v[114:117], v[154:157], v[184:187], v[114:117]
	v_mfma_f32_16x16x32_bf16 v[114:117], v[158:161], v[188:191], v[114:117]
	v_mfma_f32_16x16x32_bf16 v[102:105], v[146:149], v[198:201], v[102:105]
	v_mfma_f32_16x16x32_bf16 v[102:105], v[150:153], v[214:217], v[102:105]
	v_mfma_f32_16x16x32_bf16 v[98:101], v[154:157], v[198:201], v[98:101]
	v_mfma_f32_16x16x32_bf16 v[98:101], v[158:161], v[214:217], v[98:101]
	v_mfma_f32_16x16x32_bf16 v[86:89], v[146:149], v[218:221], v[86:89]
	v_mfma_f32_16x16x32_bf16 v[86:89], v[150:153], v[222:225], v[86:89]
	v_mfma_f32_16x16x32_bf16 v[82:85], v[154:157], v[218:221], v[82:85]
	v_mfma_f32_16x16x32_bf16 v[82:85], v[158:161], v[222:225], v[82:85]
	v_mfma_f32_16x16x32_bf16 v[70:73], v[146:149], v[226:229], v[70:73]
	v_mfma_f32_16x16x32_bf16 v[70:73], v[150:153], v[230:233], v[70:73]
	v_mfma_f32_16x16x32_bf16 v[66:69], v[154:157], v[226:229], v[66:69]
	v_mfma_f32_16x16x32_bf16 v[66:69], v[158:161], v[230:233], v[66:69]
	s_barrier
	ds_read_b128 v[184:187], v196 offset:16384
	ds_read_b128 v[188:191], v196 offset:17408
	ds_read_b128 v[198:201], v196 offset:18432
	ds_read_b128 v[214:217], v196 offset:19456
	ds_read_b128 v[218:221], v196 offset:20480
	ds_read_b128 v[222:225], v196 offset:21504
	ds_read_b128 v[226:229], v196 offset:22528
	ds_read_b128 v[230:233], v196 offset:23552
	v_lshl_add_u64 v[202:203], s[20:21], 0, v[0:1]
	s_add_i32 s20, s22, s14
	s_mov_b32 m0, s20
	s_nop 0
	s_nop 0
	global_load_lds_dwordx4 v[202:203], off
	v_lshl_add_u64 v[234:235], v[202:203], 0, s[72:73]
	s_add_i32 m0, s20, 0x2000
	s_add_i32 s20, s23, s14
	global_load_lds_dwordx4 v[234:235], off
	v_lshl_add_u64 v[234:235], v[202:203], 0, s[28:29]
	s_mov_b32 m0, s20
	s_nop 0
	global_load_lds_dwordx4 v[234:235], off
	v_lshl_add_u64 v[234:235], v[202:203], 0, s[82:83]
	s_add_i32 m0, s20, 0x2000
	s_nop 0
	global_load_lds_dwordx4 v[234:235], off
	v_lshl_add_u64 v[234:235], s[78:79], 0, v[162:163]
	s_mov_b32 m0, s43
	v_lshl_add_u64 v[236:237], v[234:235], 0, s[72:73]
	global_load_lds_dwordx4 v[234:235], off
	s_mov_b32 m0, s46
	s_nop 0
	global_load_lds_dwordx4 v[236:237], off
	s_waitcnt vmcnt(8) lgkmcnt(0)
	s_barrier
	v_mfma_f32_16x16x32_bf16 v[62:65], v[130:133], v[184:187], v[62:65]
	v_mfma_f32_16x16x32_bf16 v[62:65], v[134:137], v[188:191], v[62:65]
	v_mfma_f32_16x16x32_bf16 v[58:61], v[138:141], v[184:187], v[58:61]
	v_mfma_f32_16x16x32_bf16 v[58:61], v[142:145], v[188:191], v[58:61]
	v_mfma_f32_16x16x32_bf16 v[46:49], v[130:133], v[198:201], v[46:49]
	v_mfma_f32_16x16x32_bf16 v[46:49], v[134:137], v[214:217], v[46:49]
	v_mfma_f32_16x16x32_bf16 v[42:45], v[138:141], v[198:201], v[42:45]
	v_mfma_f32_16x16x32_bf16 v[42:45], v[142:145], v[214:217], v[42:45]
	v_mfma_f32_16x16x32_bf16 v[30:33], v[130:133], v[218:221], v[30:33]
	v_mfma_f32_16x16x32_bf16 v[30:33], v[134:137], v[222:225], v[30:33]
	v_mfma_f32_16x16x32_bf16 v[26:29], v[138:141], v[218:221], v[26:29]
	v_mfma_f32_16x16x32_bf16 v[26:29], v[142:145], v[222:225], v[26:29]
	v_mfma_f32_16x16x32_bf16 v[14:17], v[130:133], v[226:229], v[14:17]
	v_mfma_f32_16x16x32_bf16 v[14:17], v[134:137], v[230:233], v[14:17]
	v_mfma_f32_16x16x32_bf16 v[10:13], v[138:141], v[226:229], v[10:13]
	v_mfma_f32_16x16x32_bf16 v[10:13], v[142:145], v[230:233], v[10:13]
	v_mfma_f32_16x16x32_bf16 v[54:57], v[146:149], v[184:187], v[54:57]
	v_mfma_f32_16x16x32_bf16 v[54:57], v[150:153], v[188:191], v[54:57]
	v_mfma_f32_16x16x32_bf16 v[50:53], v[154:157], v[184:187], v[50:53]
	v_mfma_f32_16x16x32_bf16 v[50:53], v[158:161], v[188:191], v[50:53]
	v_mfma_f32_16x16x32_bf16 v[38:41], v[146:149], v[198:201], v[38:41]
	v_mfma_f32_16x16x32_bf16 v[38:41], v[150:153], v[214:217], v[38:41]
	v_mfma_f32_16x16x32_bf16 v[34:37], v[154:157], v[198:201], v[34:37]
	v_mfma_f32_16x16x32_bf16 v[34:37], v[158:161], v[214:217], v[34:37]
	v_mfma_f32_16x16x32_bf16 v[22:25], v[146:149], v[218:221], v[22:25]
	v_mfma_f32_16x16x32_bf16 v[22:25], v[150:153], v[222:225], v[22:25]
	v_mfma_f32_16x16x32_bf16 v[18:21], v[154:157], v[218:221], v[18:21]
	v_mfma_f32_16x16x32_bf16 v[18:21], v[158:161], v[222:225], v[18:21]
	v_mfma_f32_16x16x32_bf16 v[6:9], v[146:149], v[226:229], v[6:9]
	v_mfma_f32_16x16x32_bf16 v[6:9], v[150:153], v[230:233], v[6:9]
	v_mfma_f32_16x16x32_bf16 v[2:5], v[154:157], v[226:229], v[2:5]
	v_mfma_f32_16x16x32_bf16 v[2:5], v[158:161], v[230:233], v[2:5]
	s_barrier
	s_add_i32 s20, 0, 0x18000
	s_add_i32 s21, 0, 0x1c000
	v_add_u32_e32 v142, s20, v193
	v_add_u32_e32 v158, s21, v193
	ds_read_b128 v[130:133], v142
	ds_read_b128 v[134:137], v142 offset:1024
	ds_read_b128 v[138:141], v142 offset:2048
	ds_read_b128 v[142:145], v142 offset:3072
	ds_read_b128 v[146:149], v158
	ds_read_b128 v[150:153], v158 offset:1024
	ds_read_b128 v[154:157], v158 offset:2048
	ds_read_b128 v[158:161], v158 offset:3072
	ds_read_b128 v[184:187], v196 offset:32768
	ds_read_b128 v[188:191], v196 offset:33792
	ds_read_b128 v[198:201], v196 offset:34816
	ds_read_b128 v[214:217], v196 offset:35840
	ds_read_b128 v[218:221], v196 offset:36864
	ds_read_b128 v[222:225], v196 offset:37888
	ds_read_b128 v[226:229], v196 offset:38912
	ds_read_b128 v[230:233], v196 offset:39936
	s_mov_b32 m0, s47
	v_lshl_add_u64 v[236:237], v[234:235], 0, s[28:29]
	global_load_lds_dwordx4 v[236:237], off
	v_lshl_add_u64 v[236:237], v[234:235], 0, s[82:83]
	s_mov_b32 m0, s88
	s_nop 0
	global_load_lds_dwordx4 v[236:237], off
	s_waitcnt vmcnt(8) lgkmcnt(0)
	s_barrier
	v_mfma_f32_16x16x32_bf16 v[126:129], v[130:133], v[184:187], v[126:129]
	v_mfma_f32_16x16x32_bf16 v[126:129], v[134:137], v[188:191], v[126:129]
	v_mfma_f32_16x16x32_bf16 v[122:125], v[138:141], v[184:187], v[122:125]
	v_mfma_f32_16x16x32_bf16 v[122:125], v[142:145], v[188:191], v[122:125]
	v_mfma_f32_16x16x32_bf16 v[110:113], v[130:133], v[198:201], v[110:113]
	v_mfma_f32_16x16x32_bf16 v[110:113], v[134:137], v[214:217], v[110:113]
	v_mfma_f32_16x16x32_bf16 v[106:109], v[138:141], v[198:201], v[106:109]
	v_mfma_f32_16x16x32_bf16 v[106:109], v[142:145], v[214:217], v[106:109]
	v_mfma_f32_16x16x32_bf16 v[94:97], v[130:133], v[218:221], v[94:97]
	v_mfma_f32_16x16x32_bf16 v[94:97], v[134:137], v[222:225], v[94:97]
	v_mfma_f32_16x16x32_bf16 v[90:93], v[138:141], v[218:221], v[90:93]
	v_mfma_f32_16x16x32_bf16 v[90:93], v[142:145], v[222:225], v[90:93]
	v_mfma_f32_16x16x32_bf16 v[78:81], v[130:133], v[226:229], v[78:81]
	v_mfma_f32_16x16x32_bf16 v[78:81], v[134:137], v[230:233], v[78:81]
	v_mfma_f32_16x16x32_bf16 v[74:77], v[138:141], v[226:229], v[74:77]
	v_mfma_f32_16x16x32_bf16 v[74:77], v[142:145], v[230:233], v[74:77]
	v_mfma_f32_16x16x32_bf16 v[118:121], v[146:149], v[184:187], v[118:121]
	v_mfma_f32_16x16x32_bf16 v[118:121], v[150:153], v[188:191], v[118:121]
	v_mfma_f32_16x16x32_bf16 v[114:117], v[154:157], v[184:187], v[114:117]
	v_mfma_f32_16x16x32_bf16 v[114:117], v[158:161], v[188:191], v[114:117]
	v_mfma_f32_16x16x32_bf16 v[102:105], v[146:149], v[198:201], v[102:105]
	v_mfma_f32_16x16x32_bf16 v[102:105], v[150:153], v[214:217], v[102:105]
	v_mfma_f32_16x16x32_bf16 v[98:101], v[154:157], v[198:201], v[98:101]
	v_mfma_f32_16x16x32_bf16 v[98:101], v[158:161], v[214:217], v[98:101]
	v_mfma_f32_16x16x32_bf16 v[86:89], v[146:149], v[218:221], v[86:89]
	v_mfma_f32_16x16x32_bf16 v[86:89], v[150:153], v[222:225], v[86:89]
	v_mfma_f32_16x16x32_bf16 v[82:85], v[154:157], v[218:221], v[82:85]
	v_mfma_f32_16x16x32_bf16 v[82:85], v[158:161], v[222:225], v[82:85]
	v_mfma_f32_16x16x32_bf16 v[70:73], v[146:149], v[226:229], v[70:73]
	v_mfma_f32_16x16x32_bf16 v[70:73], v[150:153], v[230:233], v[70:73]
	v_mfma_f32_16x16x32_bf16 v[66:69], v[154:157], v[226:229], v[66:69]
	v_mfma_f32_16x16x32_bf16 v[66:69], v[158:161], v[230:233], v[66:69]
	s_barrier
	ds_read_b128 v[184:187], v196 offset:49152
	ds_read_b128 v[188:191], v196 offset:50176
	ds_read_b128 v[198:201], v196 offset:51200
	ds_read_b128 v[214:217], v196 offset:52224
	ds_read_b128 v[218:221], v196 offset:53248
	ds_read_b128 v[222:225], v196 offset:54272
	ds_read_b128 v[226:229], v196 offset:55296
	ds_read_b128 v[230:233], v196 offset:56320
	s_add_i32 s20, s20, s14
	s_mov_b32 m0, s20
	v_lshl_add_u64 v[236:237], v[202:203], 0, s[34:35]
	global_load_lds_dwordx4 v[236:237], off
	v_lshl_add_u64 v[236:237], v[202:203], 0, s[38:39]
	s_add_i32 m0, s20, 0x2000
	s_add_i32 s20, s21, s14
	global_load_lds_dwordx4 v[236:237], off
	v_lshl_add_u64 v[236:237], v[202:203], 0, s[44:45]
	s_mov_b32 m0, s20
	v_lshl_add_u64 v[202:203], v[202:203], 0, s[10:11]
	global_load_lds_dwordx4 v[236:237], off
	s_add_i32 m0, s20, 0x2000
	s_nop 0
	global_load_lds_dwordx4 v[202:203], off
	v_lshl_add_u64 v[202:203], v[234:235], 0, s[34:35]
	s_mov_b32 m0, s89
	s_nop 0
	global_load_lds_dwordx4 v[202:203], off
	v_lshl_add_u64 v[202:203], v[234:235], 0, s[38:39]
	s_mov_b32 m0, s90
	s_nop 0
	global_load_lds_dwordx4 v[202:203], off
	s_waitcnt vmcnt(8) lgkmcnt(0)
	s_barrier
	v_mfma_f32_16x16x32_bf16 v[62:65], v[130:133], v[184:187], v[62:65]
	v_mfma_f32_16x16x32_bf16 v[62:65], v[134:137], v[188:191], v[62:65]
	v_mfma_f32_16x16x32_bf16 v[58:61], v[138:141], v[184:187], v[58:61]
	v_mfma_f32_16x16x32_bf16 v[58:61], v[142:145], v[188:191], v[58:61]
	v_mfma_f32_16x16x32_bf16 v[46:49], v[130:133], v[198:201], v[46:49]
	v_mfma_f32_16x16x32_bf16 v[46:49], v[134:137], v[214:217], v[46:49]
	v_mfma_f32_16x16x32_bf16 v[42:45], v[138:141], v[198:201], v[42:45]
	v_mfma_f32_16x16x32_bf16 v[42:45], v[142:145], v[214:217], v[42:45]
	v_mfma_f32_16x16x32_bf16 v[30:33], v[130:133], v[218:221], v[30:33]
	v_mfma_f32_16x16x32_bf16 v[30:33], v[134:137], v[222:225], v[30:33]
	v_mfma_f32_16x16x32_bf16 v[26:29], v[138:141], v[218:221], v[26:29]
	v_mfma_f32_16x16x32_bf16 v[26:29], v[142:145], v[222:225], v[26:29]
	v_mfma_f32_16x16x32_bf16 v[14:17], v[130:133], v[226:229], v[14:17]
	v_mfma_f32_16x16x32_bf16 v[14:17], v[134:137], v[230:233], v[14:17]
	v_mfma_f32_16x16x32_bf16 v[10:13], v[138:141], v[226:229], v[10:13]
	v_mfma_f32_16x16x32_bf16 v[10:13], v[142:145], v[230:233], v[10:13]
	s_add_i32 vcc_hi, vcc_hi, 2
	s_add_u32 s76, s76, 0x100
	s_addc_u32 s77, s77, 0
	s_add_u32 s87, s87, 0x100
	s_addc_u32 vcc_lo, vcc_lo, 0
	s_cmp_gt_u32 vcc_hi, 13
	v_mfma_f32_16x16x32_bf16 v[54:57], v[146:149], v[184:187], v[54:57]
	v_mfma_f32_16x16x32_bf16 v[54:57], v[150:153], v[188:191], v[54:57]
	v_mfma_f32_16x16x32_bf16 v[50:53], v[154:157], v[184:187], v[50:53]
	v_mfma_f32_16x16x32_bf16 v[50:53], v[158:161], v[188:191], v[50:53]
	v_mfma_f32_16x16x32_bf16 v[38:41], v[146:149], v[198:201], v[38:41]
	v_mfma_f32_16x16x32_bf16 v[38:41], v[150:153], v[214:217], v[38:41]
	v_mfma_f32_16x16x32_bf16 v[34:37], v[154:157], v[198:201], v[34:37]
	v_mfma_f32_16x16x32_bf16 v[34:37], v[158:161], v[214:217], v[34:37]
	v_mfma_f32_16x16x32_bf16 v[22:25], v[146:149], v[218:221], v[22:25]
	v_mfma_f32_16x16x32_bf16 v[22:25], v[150:153], v[222:225], v[22:25]
	v_mfma_f32_16x16x32_bf16 v[18:21], v[154:157], v[218:221], v[18:21]
	v_mfma_f32_16x16x32_bf16 v[18:21], v[158:161], v[222:225], v[18:21]
	v_mfma_f32_16x16x32_bf16 v[6:9], v[146:149], v[226:229], v[6:9]
	v_mfma_f32_16x16x32_bf16 v[6:9], v[150:153], v[230:233], v[6:9]
	v_mfma_f32_16x16x32_bf16 v[2:5], v[154:157], v[226:229], v[2:5]
	v_mfma_f32_16x16x32_bf16 v[2:5], v[158:161], v[230:233], v[2:5]
	s_barrier
	s_cbranch_scc0 .LBB0_778
	s_setprio 0
	s_and_b64 vcc, exec, s[50:51]
	s_cbranch_vccz .LBB0_781
	s_barrier

.LBB0_850:
	s_add_i32 vcc_lo, 0, 0x10000
	v_add_u32_e32 v0, vcc_lo, v145
	s_add_i32 vcc_hi, 0, 0x14000
	ds_read_b128 v[138:141], v0
	ds_read_b128 v[146:149], v0 offset:1024
	ds_read_b128 v[150:153], v0 offset:2048
	ds_read_b128 v[158:161], v0 offset:3072
	v_add_u32_e32 v0, vcc_hi, v145
	ds_read_b128 v[182:185], v0
	ds_read_b128 v[186:189], v0 offset:1024
	ds_read_b128 v[190:193], v0 offset:2048
	ds_read_b128 v[194:197], v0 offset:3072
	ds_read_b128 v[198:201], v157
	ds_read_b128 v[214:217], v157 offset:1024
	ds_read_b128 v[218:221], v157 offset:2048
	ds_read_b128 v[222:225], v157 offset:3072
	ds_read_b128 v[226:229], v157 offset:4096
	ds_read_b128 v[230:233], v157 offset:5120
	ds_read_b128 v[234:237], v157 offset:6144
	ds_read_b128 v[238:241], v157 offset:7168
	s_add_u32 s20, s56, 0xfffc0080
	s_addc_u32 s21, s57, -1
	s_cmp_eq_u32 s91, 12
	s_cselect_b32 s59, s76, s21
	s_cselect_b32 s58, s77, s20
	s_cselect_b32 s21, s69, s87
	s_cselect_b32 s20, s79, s86
	s_add_i32 m0, s15, 0xc000
	v_lshl_add_u64 v[142:143], s[56:57], 0, v[136:137]
	global_load_lds_dwordx4 v[142:143], off
	v_lshl_add_u64 v[142:143], v[142:143], 0, s[72:73]
	s_add_i32 m0, s15, 0xe000
	s_nop 0
	global_load_lds_dwordx4 v[142:143], off
	s_waitcnt vmcnt(8) lgkmcnt(0)
	s_barrier
	v_mfma_f32_16x16x32_bf16 v[126:129], v[138:141], v[198:201], v[126:129]
	v_mfma_f32_16x16x32_bf16 v[126:129], v[146:149], v[214:217], v[126:129]
	v_mfma_f32_16x16x32_bf16 v[122:125], v[150:153], v[198:201], v[122:125]
	v_mfma_f32_16x16x32_bf16 v[122:125], v[158:161], v[214:217], v[122:125]
	v_mfma_f32_16x16x32_bf16 v[110:113], v[138:141], v[218:221], v[110:113]
	v_mfma_f32_16x16x32_bf16 v[110:113], v[146:149], v[222:225], v[110:113]
	v_mfma_f32_16x16x32_bf16 v[106:109], v[150:153], v[218:221], v[106:109]
	v_mfma_f32_16x16x32_bf16 v[106:109], v[158:161], v[222:225], v[106:109]
	v_mfma_f32_16x16x32_bf16 v[94:97], v[138:141], v[226:229], v[94:97]
	v_mfma_f32_16x16x32_bf16 v[94:97], v[146:149], v[230:233], v[94:97]
	v_mfma_f32_16x16x32_bf16 v[90:93], v[150:153], v[226:229], v[90:93]
	v_mfma_f32_16x16x32_bf16 v[90:93], v[158:161], v[230:233], v[90:93]
	v_mfma_f32_16x16x32_bf16 v[78:81], v[138:141], v[234:237], v[78:81]
	v_mfma_f32_16x16x32_bf16 v[78:81], v[146:149], v[238:241], v[78:81]
	v_mfma_f32_16x16x32_bf16 v[74:77], v[150:153], v[234:237], v[74:77]
	v_mfma_f32_16x16x32_bf16 v[74:77], v[158:161], v[238:241], v[74:77]
	v_mfma_f32_16x16x32_bf16 v[118:121], v[182:185], v[198:201], v[118:121]
	v_mfma_f32_16x16x32_bf16 v[118:121], v[186:189], v[214:217], v[118:121]
	v_mfma_f32_16x16x32_bf16 v[114:117], v[190:193], v[198:201], v[114:117]
	v_mfma_f32_16x16x32_bf16 v[114:117], v[194:197], v[214:217], v[114:117]
	v_mfma_f32_16x16x32_bf16 v[102:105], v[182:185], v[218:221], v[102:105]
	v_mfma_f32_16x16x32_bf16 v[102:105], v[186:189], v[222:225], v[102:105]
	v_mfma_f32_16x16x32_bf16 v[98:101], v[190:193], v[218:221], v[98:101]
	v_mfma_f32_16x16x32_bf16 v[98:101], v[194:197], v[222:225], v[98:101]
	v_mfma_f32_16x16x32_bf16 v[86:89], v[182:185], v[226:229], v[86:89]
	v_mfma_f32_16x16x32_bf16 v[86:89], v[186:189], v[230:233], v[86:89]
	v_mfma_f32_16x16x32_bf16 v[82:85], v[190:193], v[226:229], v[82:85]
	v_mfma_f32_16x16x32_bf16 v[82:85], v[194:197], v[230:233], v[82:85]
	v_mfma_f32_16x16x32_bf16 v[70:73], v[182:185], v[234:237], v[70:73]
	v_mfma_f32_16x16x32_bf16 v[70:73], v[186:189], v[238:241], v[70:73]
	v_mfma_f32_16x16x32_bf16 v[66:69], v[190:193], v[234:237], v[66:69]
	v_mfma_f32_16x16x32_bf16 v[66:69], v[194:197], v[238:241], v[66:69]
	s_barrier
	ds_read_b128 v[198:201], v157 offset:16384
	ds_read_b128 v[214:217], v157 offset:17408
	ds_read_b128 v[218:221], v157 offset:18432
	ds_read_b128 v[222:225], v157 offset:19456
	ds_read_b128 v[226:229], v157 offset:20480
	ds_read_b128 v[230:233], v157 offset:21504
	ds_read_b128 v[234:237], v157 offset:22528
	ds_read_b128 v[238:241], v157 offset:23552
	v_lshl_add_u64 v[142:143], s[20:21], 0, v[130:131]
	s_add_i32 s20, vcc_lo, s14
	s_mov_b32 m0, s20
	s_nop 0
	s_nop 0
	global_load_lds_dwordx4 v[142:143], off
	v_lshl_add_u64 v[162:163], v[142:143], 0, s[72:73]
	s_add_i32 m0, s20, 0x2000
	s_add_i32 s20, vcc_hi, s14
	global_load_lds_dwordx4 v[162:163], off
	v_lshl_add_u64 v[162:163], v[142:143], 0, s[28:29]
	s_mov_b32 m0, s20
	s_nop 0
	global_load_lds_dwordx4 v[162:163], off
	v_lshl_add_u64 v[162:163], v[142:143], 0, s[82:83]
	s_add_i32 m0, s20, 0x2000
	s_nop 0
	global_load_lds_dwordx4 v[162:163], off
	v_lshl_add_u64 v[162:163], s[58:59], 0, v[132:133]
	s_mov_b32 m0, s15
	v_lshl_add_u64 v[202:203], v[162:163], 0, s[72:73]
	global_load_lds_dwordx4 v[162:163], off
	s_mov_b32 m0, s42
	s_nop 0
	global_load_lds_dwordx4 v[202:203], off
	s_waitcnt vmcnt(8) lgkmcnt(0)
	s_barrier
	v_mfma_f32_16x16x32_bf16 v[62:65], v[138:141], v[198:201], v[62:65]
	v_mfma_f32_16x16x32_bf16 v[62:65], v[146:149], v[214:217], v[62:65]
	v_mfma_f32_16x16x32_bf16 v[58:61], v[150:153], v[198:201], v[58:61]
	v_mfma_f32_16x16x32_bf16 v[58:61], v[158:161], v[214:217], v[58:61]
	v_mfma_f32_16x16x32_bf16 v[46:49], v[138:141], v[218:221], v[46:49]
	v_mfma_f32_16x16x32_bf16 v[46:49], v[146:149], v[222:225], v[46:49]
	v_mfma_f32_16x16x32_bf16 v[42:45], v[150:153], v[218:221], v[42:45]
	v_mfma_f32_16x16x32_bf16 v[42:45], v[158:161], v[222:225], v[42:45]
	v_mfma_f32_16x16x32_bf16 v[30:33], v[138:141], v[226:229], v[30:33]
	v_mfma_f32_16x16x32_bf16 v[30:33], v[146:149], v[230:233], v[30:33]
	v_mfma_f32_16x16x32_bf16 v[26:29], v[150:153], v[226:229], v[26:29]
	v_mfma_f32_16x16x32_bf16 v[26:29], v[158:161], v[230:233], v[26:29]
	v_mfma_f32_16x16x32_bf16 v[14:17], v[138:141], v[234:237], v[14:17]
	v_mfma_f32_16x16x32_bf16 v[14:17], v[146:149], v[238:241], v[14:17]
	v_mfma_f32_16x16x32_bf16 v[10:13], v[150:153], v[234:237], v[10:13]
	v_mfma_f32_16x16x32_bf16 v[10:13], v[158:161], v[238:241], v[10:13]
	v_mfma_f32_16x16x32_bf16 v[54:57], v[182:185], v[198:201], v[54:57]
	v_mfma_f32_16x16x32_bf16 v[54:57], v[186:189], v[214:217], v[54:57]
	v_mfma_f32_16x16x32_bf16 v[50:53], v[190:193], v[198:201], v[50:53]
	v_mfma_f32_16x16x32_bf16 v[50:53], v[194:197], v[214:217], v[50:53]
	v_mfma_f32_16x16x32_bf16 v[38:41], v[182:185], v[218:221], v[38:41]
	v_mfma_f32_16x16x32_bf16 v[38:41], v[186:189], v[222:225], v[38:41]
	v_mfma_f32_16x16x32_bf16 v[34:37], v[190:193], v[218:221], v[34:37]
	v_mfma_f32_16x16x32_bf16 v[34:37], v[194:197], v[222:225], v[34:37]
	v_mfma_f32_16x16x32_bf16 v[22:25], v[182:185], v[226:229], v[22:25]
	v_mfma_f32_16x16x32_bf16 v[22:25], v[186:189], v[230:233], v[22:25]
	v_mfma_f32_16x16x32_bf16 v[18:21], v[190:193], v[226:229], v[18:21]
	v_mfma_f32_16x16x32_bf16 v[18:21], v[194:197], v[230:233], v[18:21]
	v_mfma_f32_16x16x32_bf16 v[6:9], v[182:185], v[234:237], v[6:9]
	v_mfma_f32_16x16x32_bf16 v[6:9], v[186:189], v[238:241], v[6:9]
	v_mfma_f32_16x16x32_bf16 v[2:5], v[190:193], v[234:237], v[2:5]
	v_mfma_f32_16x16x32_bf16 v[2:5], v[194:197], v[238:241], v[2:5]
	s_barrier
	s_add_i32 s20, 0, 0x18000
	v_add_u32_e32 v0, s20, v145
	s_add_i32 s21, 0, 0x1c000
	ds_read_b128 v[138:141], v0
	ds_read_b128 v[146:149], v0 offset:1024
	ds_read_b128 v[150:153], v0 offset:2048
	ds_read_b128 v[158:161], v0 offset:3072
	v_add_u32_e32 v0, s21, v145
	ds_read_b128 v[182:185], v0
	ds_read_b128 v[186:189], v0 offset:1024
	ds_read_b128 v[190:193], v0 offset:2048
	ds_read_b128 v[194:197], v0 offset:3072
	ds_read_b128 v[198:201], v157 offset:32768
	ds_read_b128 v[214:217], v157 offset:33792
	ds_read_b128 v[218:221], v157 offset:34816
	ds_read_b128 v[222:225], v157 offset:35840
	ds_read_b128 v[226:229], v157 offset:36864
	ds_read_b128 v[230:233], v157 offset:37888
	ds_read_b128 v[234:237], v157 offset:38912
	ds_read_b128 v[238:241], v157 offset:39936
	s_mov_b32 m0, s43
	v_lshl_add_u64 v[202:203], v[162:163], 0, s[28:29]
	global_load_lds_dwordx4 v[202:203], off
	v_lshl_add_u64 v[202:203], v[162:163], 0, s[82:83]
	s_mov_b32 m0, s46
	s_nop 0
	global_load_lds_dwordx4 v[202:203], off
	s_waitcnt vmcnt(8) lgkmcnt(0)
	s_barrier
	v_mfma_f32_16x16x32_bf16 v[126:129], v[138:141], v[198:201], v[126:129]
	v_mfma_f32_16x16x32_bf16 v[126:129], v[146:149], v[214:217], v[126:129]
	v_mfma_f32_16x16x32_bf16 v[122:125], v[150:153], v[198:201], v[122:125]
	v_mfma_f32_16x16x32_bf16 v[122:125], v[158:161], v[214:217], v[122:125]
	v_mfma_f32_16x16x32_bf16 v[110:113], v[138:141], v[218:221], v[110:113]
	v_mfma_f32_16x16x32_bf16 v[110:113], v[146:149], v[222:225], v[110:113]
	v_mfma_f32_16x16x32_bf16 v[106:109], v[150:153], v[218:221], v[106:109]
	v_mfma_f32_16x16x32_bf16 v[106:109], v[158:161], v[222:225], v[106:109]
	v_mfma_f32_16x16x32_bf16 v[94:97], v[138:141], v[226:229], v[94:97]
	v_mfma_f32_16x16x32_bf16 v[94:97], v[146:149], v[230:233], v[94:97]
	v_mfma_f32_16x16x32_bf16 v[90:93], v[150:153], v[226:229], v[90:93]
	v_mfma_f32_16x16x32_bf16 v[90:93], v[158:161], v[230:233], v[90:93]
	v_mfma_f32_16x16x32_bf16 v[78:81], v[138:141], v[234:237], v[78:81]
	v_mfma_f32_16x16x32_bf16 v[78:81], v[146:149], v[238:241], v[78:81]
	v_mfma_f32_16x16x32_bf16 v[74:77], v[150:153], v[234:237], v[74:77]
	v_mfma_f32_16x16x32_bf16 v[74:77], v[158:161], v[238:241], v[74:77]
	v_mfma_f32_16x16x32_bf16 v[118:121], v[182:185], v[198:201], v[118:121]
	v_mfma_f32_16x16x32_bf16 v[118:121], v[186:189], v[214:217], v[118:121]
	v_mfma_f32_16x16x32_bf16 v[114:117], v[190:193], v[198:201], v[114:117]
	v_mfma_f32_16x16x32_bf16 v[114:117], v[194:197], v[214:217], v[114:117]
	v_mfma_f32_16x16x32_bf16 v[102:105], v[182:185], v[218:221], v[102:105]
	v_mfma_f32_16x16x32_bf16 v[102:105], v[186:189], v[222:225], v[102:105]
	v_mfma_f32_16x16x32_bf16 v[98:101], v[190:193], v[218:221], v[98:101]
	v_mfma_f32_16x16x32_bf16 v[98:101], v[194:197], v[222:225], v[98:101]
	v_mfma_f32_16x16x32_bf16 v[86:89], v[182:185], v[226:229], v[86:89]
	v_mfma_f32_16x16x32_bf16 v[86:89], v[186:189], v[230:233], v[86:89]
	v_mfma_f32_16x16x32_bf16 v[82:85], v[190:193], v[226:229], v[82:85]
	v_mfma_f32_16x16x32_bf16 v[82:85], v[194:197], v[230:233], v[82:85]
	v_mfma_f32_16x16x32_bf16 v[70:73], v[182:185], v[234:237], v[70:73]
	v_mfma_f32_16x16x32_bf16 v[70:73], v[186:189], v[238:241], v[70:73]
	v_mfma_f32_16x16x32_bf16 v[66:69], v[190:193], v[234:237], v[66:69]
	v_mfma_f32_16x16x32_bf16 v[66:69], v[194:197], v[238:241], v[66:69]
	s_barrier
	ds_read_b128 v[198:201], v157 offset:49152
	ds_read_b128 v[214:217], v157 offset:50176
	ds_read_b128 v[218:221], v157 offset:51200
	ds_read_b128 v[222:225], v157 offset:52224
	ds_read_b128 v[226:229], v157 offset:53248
	ds_read_b128 v[230:233], v157 offset:54272
	ds_read_b128 v[234:237], v157 offset:55296
	ds_read_b128 v[238:241], v157 offset:56320
	s_add_i32 s20, s20, s14
	s_mov_b32 m0, s20
	v_lshl_add_u64 v[202:203], v[142:143], 0, s[34:35]
	global_load_lds_dwordx4 v[202:203], off
	v_lshl_add_u64 v[202:203], v[142:143], 0, s[38:39]
	s_add_i32 m0, s20, 0x2000
	s_add_i32 s20, s21, s14
	global_load_lds_dwordx4 v[202:203], off
	v_lshl_add_u64 v[202:203], v[142:143], 0, s[44:45]
	s_mov_b32 m0, s20
	v_lshl_add_u64 v[142:143], v[142:143], 0, s[10:11]
	global_load_lds_dwordx4 v[202:203], off
	s_add_i32 m0, s20, 0x2000
	s_nop 0
	global_load_lds_dwordx4 v[142:143], off
	v_lshl_add_u64 v[142:143], v[162:163], 0, s[34:35]
	s_mov_b32 m0, s47
	s_nop 0
	global_load_lds_dwordx4 v[142:143], off
	v_lshl_add_u64 v[142:143], v[162:163], 0, s[38:39]
	s_mov_b32 m0, s96
	s_nop 0
	global_load_lds_dwordx4 v[142:143], off
	s_waitcnt vmcnt(8) lgkmcnt(0)
	s_barrier
	v_mfma_f32_16x16x32_bf16 v[62:65], v[138:141], v[198:201], v[62:65]
	v_mfma_f32_16x16x32_bf16 v[62:65], v[146:149], v[214:217], v[62:65]
	v_mfma_f32_16x16x32_bf16 v[58:61], v[150:153], v[198:201], v[58:61]
	v_mfma_f32_16x16x32_bf16 v[58:61], v[158:161], v[214:217], v[58:61]
	v_mfma_f32_16x16x32_bf16 v[46:49], v[138:141], v[218:221], v[46:49]
	v_mfma_f32_16x16x32_bf16 v[46:49], v[146:149], v[222:225], v[46:49]
	v_mfma_f32_16x16x32_bf16 v[42:45], v[150:153], v[218:221], v[42:45]
	v_mfma_f32_16x16x32_bf16 v[42:45], v[158:161], v[222:225], v[42:45]
	v_mfma_f32_16x16x32_bf16 v[30:33], v[138:141], v[226:229], v[30:33]
	v_mfma_f32_16x16x32_bf16 v[30:33], v[146:149], v[230:233], v[30:33]
	v_mfma_f32_16x16x32_bf16 v[26:29], v[150:153], v[226:229], v[26:29]
	v_mfma_f32_16x16x32_bf16 v[26:29], v[158:161], v[230:233], v[26:29]
	v_mfma_f32_16x16x32_bf16 v[14:17], v[138:141], v[234:237], v[14:17]
	v_mfma_f32_16x16x32_bf16 v[14:17], v[146:149], v[238:241], v[14:17]
	v_mfma_f32_16x16x32_bf16 v[10:13], v[150:153], v[234:237], v[10:13]
	v_mfma_f32_16x16x32_bf16 v[10:13], v[158:161], v[238:241], v[10:13]
	s_add_i32 s91, s91, 2
	s_add_u32 s56, s56, 0x100
	s_addc_u32 s57, s57, 0
	s_add_u32 s86, s86, 0x100
	s_addc_u32 s87, s87, 0
	s_cmp_gt_u32 s91, 13
	v_mfma_f32_16x16x32_bf16 v[54:57], v[182:185], v[198:201], v[54:57]
	v_mfma_f32_16x16x32_bf16 v[54:57], v[186:189], v[214:217], v[54:57]
	v_mfma_f32_16x16x32_bf16 v[50:53], v[190:193], v[198:201], v[50:53]
	v_mfma_f32_16x16x32_bf16 v[50:53], v[194:197], v[214:217], v[50:53]
	v_mfma_f32_16x16x32_bf16 v[38:41], v[182:185], v[218:221], v[38:41]
	v_mfma_f32_16x16x32_bf16 v[38:41], v[186:189], v[222:225], v[38:41]
	v_mfma_f32_16x16x32_bf16 v[34:37], v[190:193], v[218:221], v[34:37]
	v_mfma_f32_16x16x32_bf16 v[34:37], v[194:197], v[222:225], v[34:37]
	v_mfma_f32_16x16x32_bf16 v[22:25], v[182:185], v[226:229], v[22:25]
	v_mfma_f32_16x16x32_bf16 v[22:25], v[186:189], v[230:233], v[22:25]
	v_mfma_f32_16x16x32_bf16 v[18:21], v[190:193], v[226:229], v[18:21]
	v_mfma_f32_16x16x32_bf16 v[18:21], v[194:197], v[230:233], v[18:21]
	v_mfma_f32_16x16x32_bf16 v[6:9], v[182:185], v[234:237], v[6:9]
	v_mfma_f32_16x16x32_bf16 v[6:9], v[186:189], v[238:241], v[6:9]
	v_mfma_f32_16x16x32_bf16 v[2:5], v[190:193], v[234:237], v[2:5]
	v_mfma_f32_16x16x32_bf16 v[2:5], v[194:197], v[238:241], v[2:5]
	s_barrier
	s_cbranch_scc0 .LBB0_850
	s_setprio 0
	s_and_b64 vcc, exec, s[62:63]
	s_cbranch_vccz .LBB0_853
	s_barrier

.LBB0_1052:
	s_add_u32 s78, s58, s68
	s_addc_u32 s79, s59, s69
	s_add_u32 s76, s78, 0x100
	s_addc_u32 s77, s79, 0
	s_and_b64 s[20:21], s[62:63], exec
	s_cselect_b32 s76, s86, s76
	s_cselect_b32 s77, s41, s77
	s_add_u32 s20, s56, s68
	s_addc_u32 s21, s57, s69
	s_add_u32 s68, s20, 0x100
	s_addc_u32 s69, s21, 0
	s_add_i32 vcc_lo, 0, 0x10000
	s_and_b64 s[20:21], s[62:63], exec
	s_cselect_b32 s62, s87, s68
	s_cselect_b32 s63, s49, s69
	s_add_i32 s21, 0, 0x14000
	v_add_u32_e32 v148, vcc_lo, v133
	v_add_u32_e32 v182, s21, v133
	ds_read_b128 v[136:139], v148
	ds_read_b128 v[140:143], v148 offset:1024
	ds_read_b128 v[144:147], v148 offset:2048
	ds_read_b128 v[148:151], v148 offset:3072
	ds_read_b128 v[152:155], v182
	ds_read_b128 v[156:159], v182 offset:1024
	ds_read_b128 v[160:163], v182 offset:2048
	ds_read_b128 v[182:185], v182 offset:3072
	s_add_i32 s93, 0, 0x18000
	s_add_i32 s69, 0, 0x1c000
	s_add_i32 s20, s93, s46
	s_add_i32 s97, vcc_lo, s46
	s_add_i32 s95, s21, s46
	s_add_i32 s68, s20, 0x2000
	s_add_i32 vcc_hi, s69, s46
	s_add_i32 m0, s22, 0xc000
	s_add_i32 s47, s22, 0xe000
	s_add_i32 s96, s97, 0x2000
	s_add_i32 s94, s95, 0x2000
	s_add_i32 vcc_lo, vcc_hi, 0x2000
	v_lshl_add_u64 v[202:203], s[78:79], 0, v[130:131]
	v_lshl_add_u64 v[230:231], v[202:203], 0, s[80:81]
	ds_read_b128 v[186:189], v135
	ds_read_b128 v[190:193], v135 offset:1024
	ds_read_b128 v[194:197], v135 offset:2048
	ds_read_b128 v[198:201], v135 offset:3072
	ds_read_b128 v[214:217], v135 offset:4096
	ds_read_b128 v[218:221], v135 offset:5120
	ds_read_b128 v[222:225], v135 offset:6144
	ds_read_b128 v[226:229], v135 offset:7168
	global_load_lds_dwordx4 v[230:231], off
	v_lshl_add_u64 v[202:203], v[202:203], 0, s[30:31]
	s_mov_b32 m0, s47
	s_nop 0
	global_load_lds_dwordx4 v[202:203], off
	s_waitcnt vmcnt(8) lgkmcnt(0)
	s_barrier
	v_mfma_f32_16x16x32_bf16 v[126:129], v[136:139], v[186:189], v[126:129]
	v_mfma_f32_16x16x32_bf16 v[126:129], v[140:143], v[190:193], v[126:129]
	v_mfma_f32_16x16x32_bf16 v[122:125], v[144:147], v[186:189], v[122:125]
	v_mfma_f32_16x16x32_bf16 v[122:125], v[148:151], v[190:193], v[122:125]
	v_mfma_f32_16x16x32_bf16 v[118:121], v[136:139], v[194:197], v[118:121]
	v_mfma_f32_16x16x32_bf16 v[118:121], v[140:143], v[198:201], v[118:121]
	v_mfma_f32_16x16x32_bf16 v[110:113], v[144:147], v[194:197], v[110:113]
	v_mfma_f32_16x16x32_bf16 v[110:113], v[148:151], v[198:201], v[110:113]
	v_mfma_f32_16x16x32_bf16 v[102:105], v[136:139], v[214:217], v[102:105]
	v_mfma_f32_16x16x32_bf16 v[102:105], v[140:143], v[218:221], v[102:105]
	v_mfma_f32_16x16x32_bf16 v[94:97], v[144:147], v[214:217], v[94:97]
	v_mfma_f32_16x16x32_bf16 v[94:97], v[148:151], v[218:221], v[94:97]
	v_mfma_f32_16x16x32_bf16 v[86:89], v[136:139], v[222:225], v[86:89]
	v_mfma_f32_16x16x32_bf16 v[86:89], v[140:143], v[226:229], v[86:89]
	v_mfma_f32_16x16x32_bf16 v[78:81], v[144:147], v[222:225], v[78:81]
	v_mfma_f32_16x16x32_bf16 v[78:81], v[148:151], v[226:229], v[78:81]
	v_mfma_f32_16x16x32_bf16 v[114:117], v[152:155], v[186:189], v[114:117]
	v_mfma_f32_16x16x32_bf16 v[114:117], v[156:159], v[190:193], v[114:117]
	v_mfma_f32_16x16x32_bf16 v[106:109], v[160:163], v[186:189], v[106:109]
	v_mfma_f32_16x16x32_bf16 v[106:109], v[182:185], v[190:193], v[106:109]
	v_mfma_f32_16x16x32_bf16 v[98:101], v[152:155], v[194:197], v[98:101]
	v_mfma_f32_16x16x32_bf16 v[98:101], v[156:159], v[198:201], v[98:101]
	v_mfma_f32_16x16x32_bf16 v[90:93], v[160:163], v[194:197], v[90:93]
	v_mfma_f32_16x16x32_bf16 v[90:93], v[182:185], v[198:201], v[90:93]
	v_mfma_f32_16x16x32_bf16 v[82:85], v[152:155], v[214:217], v[82:85]
	v_mfma_f32_16x16x32_bf16 v[82:85], v[156:159], v[218:221], v[82:85]
	v_mfma_f32_16x16x32_bf16 v[74:77], v[160:163], v[214:217], v[74:77]
	v_mfma_f32_16x16x32_bf16 v[74:77], v[182:185], v[218:221], v[74:77]
	v_mfma_f32_16x16x32_bf16 v[70:73], v[152:155], v[222:225], v[70:73]
	v_mfma_f32_16x16x32_bf16 v[70:73], v[156:159], v[226:229], v[70:73]
	v_mfma_f32_16x16x32_bf16 v[66:69], v[160:163], v[222:225], v[66:69]
	v_mfma_f32_16x16x32_bf16 v[66:69], v[182:185], v[226:229], v[66:69]
	s_barrier
	s_mov_b32 m0, s97
	v_lshl_add_u64 v[202:203], s[62:63], 0, v[0:1]
	ds_read_b128 v[186:189], v135 offset:16384
	ds_read_b128 v[190:193], v135 offset:17408
	ds_read_b128 v[194:197], v135 offset:18432
	ds_read_b128 v[198:201], v135 offset:19456
	ds_read_b128 v[214:217], v135 offset:20480
	ds_read_b128 v[218:221], v135 offset:21504
	ds_read_b128 v[222:225], v135 offset:22528
	ds_read_b128 v[226:229], v135 offset:23552
	global_load_lds_dwordx4 v[202:203], off
	v_lshl_add_u64 v[230:231], v[202:203], 0, s[36:37]
	s_mov_b32 m0, s96
	s_nop 0
	global_load_lds_dwordx4 v[230:231], off
	v_lshl_add_u64 v[230:231], v[202:203], 0, s[64:65]
	s_mov_b32 m0, s95
	s_nop 0
	global_load_lds_dwordx4 v[230:231], off
	v_lshl_add_u64 v[230:231], v[202:203], 0, s[8:9]
	s_mov_b32 m0, s94
	s_nop 0
	global_load_lds_dwordx4 v[230:231], off
	v_lshl_add_u64 v[230:231], s[76:77], 0, v[130:131]
	s_mov_b32 m0, s22
	v_lshl_add_u64 v[232:233], v[230:231], 0, s[36:37]
	global_load_lds_dwordx4 v[230:231], off
	s_mov_b32 m0, s88
	s_nop 0
	global_load_lds_dwordx4 v[232:233], off
	s_waitcnt vmcnt(8) lgkmcnt(0)
	s_barrier
	v_mfma_f32_16x16x32_bf16 v[62:65], v[136:139], v[186:189], v[62:65]
	v_mfma_f32_16x16x32_bf16 v[62:65], v[140:143], v[190:193], v[62:65]
	v_mfma_f32_16x16x32_bf16 v[58:61], v[144:147], v[186:189], v[58:61]
	v_mfma_f32_16x16x32_bf16 v[58:61], v[148:151], v[190:193], v[58:61]
	v_mfma_f32_16x16x32_bf16 v[54:57], v[136:139], v[194:197], v[54:57]
	v_mfma_f32_16x16x32_bf16 v[54:57], v[140:143], v[198:201], v[54:57]
	v_mfma_f32_16x16x32_bf16 v[46:49], v[144:147], v[194:197], v[46:49]
	v_mfma_f32_16x16x32_bf16 v[46:49], v[148:151], v[198:201], v[46:49]
	v_mfma_f32_16x16x32_bf16 v[38:41], v[136:139], v[214:217], v[38:41]
	v_mfma_f32_16x16x32_bf16 v[38:41], v[140:143], v[218:221], v[38:41]
	v_mfma_f32_16x16x32_bf16 v[30:33], v[144:147], v[214:217], v[30:33]
	v_mfma_f32_16x16x32_bf16 v[30:33], v[148:151], v[218:221], v[30:33]
	v_mfma_f32_16x16x32_bf16 v[22:25], v[136:139], v[222:225], v[22:25]
	v_mfma_f32_16x16x32_bf16 v[22:25], v[140:143], v[226:229], v[22:25]
	v_mfma_f32_16x16x32_bf16 v[14:17], v[144:147], v[222:225], v[14:17]
	v_mfma_f32_16x16x32_bf16 v[14:17], v[148:151], v[226:229], v[14:17]
	v_mfma_f32_16x16x32_bf16 v[50:53], v[152:155], v[186:189], v[50:53]
	v_mfma_f32_16x16x32_bf16 v[50:53], v[156:159], v[190:193], v[50:53]
	v_mfma_f32_16x16x32_bf16 v[42:45], v[160:163], v[186:189], v[42:45]
	v_mfma_f32_16x16x32_bf16 v[42:45], v[182:185], v[190:193], v[42:45]
	v_mfma_f32_16x16x32_bf16 v[34:37], v[152:155], v[194:197], v[34:37]
	v_mfma_f32_16x16x32_bf16 v[34:37], v[156:159], v[198:201], v[34:37]
	v_mfma_f32_16x16x32_bf16 v[26:29], v[160:163], v[194:197], v[26:29]
	v_mfma_f32_16x16x32_bf16 v[26:29], v[182:185], v[198:201], v[26:29]
	v_mfma_f32_16x16x32_bf16 v[18:21], v[152:155], v[214:217], v[18:21]
	v_mfma_f32_16x16x32_bf16 v[18:21], v[156:159], v[218:221], v[18:21]
	v_mfma_f32_16x16x32_bf16 v[10:13], v[160:163], v[214:217], v[10:13]
	v_mfma_f32_16x16x32_bf16 v[10:13], v[182:185], v[218:221], v[10:13]
	v_mfma_f32_16x16x32_bf16 v[6:9], v[152:155], v[222:225], v[6:9]
	v_mfma_f32_16x16x32_bf16 v[6:9], v[156:159], v[226:229], v[6:9]
	v_mfma_f32_16x16x32_bf16 v[2:5], v[160:163], v[222:225], v[2:5]
	v_mfma_f32_16x16x32_bf16 v[2:5], v[182:185], v[226:229], v[2:5]
	s_barrier
	v_add_u32_e32 v148, s93, v133
	v_add_u32_e32 v182, s69, v133
	ds_read_b128 v[136:139], v148
	ds_read_b128 v[140:143], v148 offset:1024
	ds_read_b128 v[144:147], v148 offset:2048
	ds_read_b128 v[148:151], v148 offset:3072
	ds_read_b128 v[152:155], v182
	ds_read_b128 v[156:159], v182 offset:1024
	ds_read_b128 v[160:163], v182 offset:2048
	ds_read_b128 v[182:185], v182 offset:3072
	s_mov_b32 m0, s89
	v_lshl_add_u64 v[232:233], v[230:231], 0, s[64:65]
	ds_read_b128 v[186:189], v135 offset:32768
	ds_read_b128 v[190:193], v135 offset:33792
	ds_read_b128 v[194:197], v135 offset:34816
	ds_read_b128 v[198:201], v135 offset:35840
	ds_read_b128 v[214:217], v135 offset:36864
	ds_read_b128 v[218:221], v135 offset:37888
	ds_read_b128 v[222:225], v135 offset:38912
	ds_read_b128 v[226:229], v135 offset:39936
	global_load_lds_dwordx4 v[232:233], off
	v_lshl_add_u64 v[232:233], v[230:231], 0, s[8:9]
	s_mov_b32 m0, s90
	s_nop 0
	global_load_lds_dwordx4 v[232:233], off
	s_waitcnt vmcnt(8) lgkmcnt(0)
	s_barrier
	v_mfma_f32_16x16x32_bf16 v[126:129], v[136:139], v[186:189], v[126:129]
	v_mfma_f32_16x16x32_bf16 v[126:129], v[140:143], v[190:193], v[126:129]
	v_mfma_f32_16x16x32_bf16 v[122:125], v[144:147], v[186:189], v[122:125]
	v_mfma_f32_16x16x32_bf16 v[122:125], v[148:151], v[190:193], v[122:125]
	v_mfma_f32_16x16x32_bf16 v[118:121], v[136:139], v[194:197], v[118:121]
	v_mfma_f32_16x16x32_bf16 v[118:121], v[140:143], v[198:201], v[118:121]
	v_mfma_f32_16x16x32_bf16 v[110:113], v[144:147], v[194:197], v[110:113]
	v_mfma_f32_16x16x32_bf16 v[110:113], v[148:151], v[198:201], v[110:113]
	v_mfma_f32_16x16x32_bf16 v[102:105], v[136:139], v[214:217], v[102:105]
	v_mfma_f32_16x16x32_bf16 v[102:105], v[140:143], v[218:221], v[102:105]
	v_mfma_f32_16x16x32_bf16 v[94:97], v[144:147], v[214:217], v[94:97]
	v_mfma_f32_16x16x32_bf16 v[94:97], v[148:151], v[218:221], v[94:97]
	v_mfma_f32_16x16x32_bf16 v[86:89], v[136:139], v[222:225], v[86:89]
	v_mfma_f32_16x16x32_bf16 v[86:89], v[140:143], v[226:229], v[86:89]
	v_mfma_f32_16x16x32_bf16 v[78:81], v[144:147], v[222:225], v[78:81]
	v_mfma_f32_16x16x32_bf16 v[78:81], v[148:151], v[226:229], v[78:81]
	v_mfma_f32_16x16x32_bf16 v[114:117], v[152:155], v[186:189], v[114:117]
	v_mfma_f32_16x16x32_bf16 v[114:117], v[156:159], v[190:193], v[114:117]
	v_mfma_f32_16x16x32_bf16 v[106:109], v[160:163], v[186:189], v[106:109]
	v_mfma_f32_16x16x32_bf16 v[106:109], v[182:185], v[190:193], v[106:109]
	v_mfma_f32_16x16x32_bf16 v[98:101], v[152:155], v[194:197], v[98:101]
	v_mfma_f32_16x16x32_bf16 v[98:101], v[156:159], v[198:201], v[98:101]
	v_mfma_f32_16x16x32_bf16 v[90:93], v[160:163], v[194:197], v[90:93]
	v_mfma_f32_16x16x32_bf16 v[90:93], v[182:185], v[198:201], v[90:93]
	v_mfma_f32_16x16x32_bf16 v[82:85], v[152:155], v[214:217], v[82:85]
	v_mfma_f32_16x16x32_bf16 v[82:85], v[156:159], v[218:221], v[82:85]
	v_mfma_f32_16x16x32_bf16 v[74:77], v[160:163], v[214:217], v[74:77]
	v_mfma_f32_16x16x32_bf16 v[74:77], v[182:185], v[218:221], v[74:77]
	v_mfma_f32_16x16x32_bf16 v[70:73], v[152:155], v[222:225], v[70:73]
	v_mfma_f32_16x16x32_bf16 v[70:73], v[156:159], v[226:229], v[70:73]
	v_mfma_f32_16x16x32_bf16 v[66:69], v[160:163], v[222:225], v[66:69]
	v_mfma_f32_16x16x32_bf16 v[66:69], v[182:185], v[226:229], v[66:69]
	s_barrier
	s_mov_b32 m0, s20
	v_lshl_add_u64 v[232:233], v[202:203], 0, s[34:35]
	ds_read_b128 v[186:189], v135 offset:49152
	ds_read_b128 v[190:193], v135 offset:50176
	ds_read_b128 v[194:197], v135 offset:51200
	ds_read_b128 v[198:201], v135 offset:52224
	ds_read_b128 v[214:217], v135 offset:53248
	ds_read_b128 v[218:221], v135 offset:54272
	ds_read_b128 v[222:225], v135 offset:55296
	ds_read_b128 v[226:229], v135 offset:56320
	global_load_lds_dwordx4 v[232:233], off
	v_lshl_add_u64 v[232:233], v[202:203], 0, s[70:71]
	s_mov_b32 m0, s68
	s_nop 0
	global_load_lds_dwordx4 v[232:233], off
	v_lshl_add_u64 v[232:233], v[202:203], 0, s[80:81]
	s_mov_b32 m0, vcc_hi
	v_lshl_add_u64 v[202:203], v[202:203], 0, s[30:31]
	global_load_lds_dwordx4 v[232:233], off
	s_mov_b32 m0, vcc_lo
	s_nop 0
	global_load_lds_dwordx4 v[202:203], off
	v_lshl_add_u64 v[202:203], v[230:231], 0, s[34:35]
	s_mov_b32 m0, s91
	s_nop 0
	global_load_lds_dwordx4 v[202:203], off
	v_lshl_add_u64 v[202:203], v[230:231], 0, s[70:71]
	s_mov_b32 m0, s92
	s_nop 0
	global_load_lds_dwordx4 v[202:203], off
	s_waitcnt vmcnt(8) lgkmcnt(0)
	s_barrier
	v_mfma_f32_16x16x32_bf16 v[62:65], v[136:139], v[186:189], v[62:65]
	v_mfma_f32_16x16x32_bf16 v[62:65], v[140:143], v[190:193], v[62:65]
	v_mfma_f32_16x16x32_bf16 v[58:61], v[144:147], v[186:189], v[58:61]
	v_mfma_f32_16x16x32_bf16 v[58:61], v[148:151], v[190:193], v[58:61]
	v_mfma_f32_16x16x32_bf16 v[54:57], v[136:139], v[194:197], v[54:57]
	v_mfma_f32_16x16x32_bf16 v[54:57], v[140:143], v[198:201], v[54:57]
	v_mfma_f32_16x16x32_bf16 v[46:49], v[144:147], v[194:197], v[46:49]
	v_mfma_f32_16x16x32_bf16 v[46:49], v[148:151], v[198:201], v[46:49]
	v_mfma_f32_16x16x32_bf16 v[38:41], v[136:139], v[214:217], v[38:41]
	v_mfma_f32_16x16x32_bf16 v[38:41], v[140:143], v[218:221], v[38:41]
	v_mfma_f32_16x16x32_bf16 v[30:33], v[144:147], v[214:217], v[30:33]
	v_mfma_f32_16x16x32_bf16 v[30:33], v[148:151], v[218:221], v[30:33]
	v_mfma_f32_16x16x32_bf16 v[22:25], v[136:139], v[222:225], v[22:25]
	v_mfma_f32_16x16x32_bf16 v[22:25], v[140:143], v[226:229], v[22:25]
	v_mfma_f32_16x16x32_bf16 v[14:17], v[144:147], v[222:225], v[14:17]
	v_mfma_f32_16x16x32_bf16 v[14:17], v[148:151], v[226:229], v[14:17]
	v_mfma_f32_16x16x32_bf16 v[50:53], v[152:155], v[186:189], v[50:53]
	v_mfma_f32_16x16x32_bf16 v[50:53], v[156:159], v[190:193], v[50:53]
	v_mfma_f32_16x16x32_bf16 v[42:45], v[160:163], v[186:189], v[42:45]
	v_mfma_f32_16x16x32_bf16 v[42:45], v[182:185], v[190:193], v[42:45]
	v_mfma_f32_16x16x32_bf16 v[34:37], v[152:155], v[194:197], v[34:37]
	v_mfma_f32_16x16x32_bf16 v[34:37], v[156:159], v[198:201], v[34:37]
	v_mfma_f32_16x16x32_bf16 v[26:29], v[160:163], v[194:197], v[26:29]
	v_mfma_f32_16x16x32_bf16 v[26:29], v[182:185], v[198:201], v[26:29]
	v_mfma_f32_16x16x32_bf16 v[18:21], v[152:155], v[214:217], v[18:21]
	v_mfma_f32_16x16x32_bf16 v[18:21], v[156:159], v[218:221], v[18:21]
	v_mfma_f32_16x16x32_bf16 v[10:13], v[160:163], v[214:217], v[10:13]
	v_mfma_f32_16x16x32_bf16 v[10:13], v[182:185], v[218:221], v[10:13]
	v_mfma_f32_16x16x32_bf16 v[6:9], v[152:155], v[222:225], v[6:9]
	v_mfma_f32_16x16x32_bf16 v[6:9], v[156:159], v[226:229], v[6:9]
	v_mfma_f32_16x16x32_bf16 v[2:5], v[160:163], v[222:225], v[2:5]
	v_mfma_f32_16x16x32_bf16 v[2:5], v[182:185], v[226:229], v[2:5]
	s_barrier
	s_andn2_b64 vcc, exec, s[60:61]
	s_mov_b64 s[62:63], -1
	s_mov_b64 s[60:61], 0
	s_mov_b64 s[68:69], 0x100
	s_cbranch_vccz .LBB0_1052
	s_and_b64 vcc, exec, s[6:7]
	s_cbranch_vccz .LBB0_1055
	s_barrier
